# v15: v13 + s_nop before LDS-DMA removed by placing the address VALU between the m0 write and the load (46 sites)
# speedup vs baseline: 1.0021x; 1.0021x over previous
.LBB0_271:
	s_add_u32 s26, s14, 0xfffc0080
	s_addc_u32 s27, s15, -1
	s_add_i32 s54, 0, 0x10000
	s_cmp_eq_u32 s53, 12
	s_cselect_b32 s29, s21, s27
	s_cselect_b32 s28, s49, s26
	v_add_u32_e32 v154, s54, v141
	s_cselect_b32 s27, s19, s52
	s_cselect_b32 s26, s50, s51
	s_add_i32 s56, 0, 0x14000
	ds_read_b128 v[146:149], v154
	ds_read_b128 v[150:153], v154 offset:1024
	ds_read_b128 v[162:165], v154 offset:2048
	ds_read_b128 v[166:169], v154 offset:3072
	v_add_u32_e32 v154, s56, v141
	ds_read_b128 v[170:173], v154
	ds_read_b128 v[186:189], v154 offset:1024
	ds_read_b128 v[190:193], v154 offset:2048
	ds_read_b128 v[194:197], v154 offset:3072
	v_lshl_add_u64 v[154:155], s[14:15], 0, v[136:137]
	s_add_i32 m0, s37, 0xc000
	ds_read_b128 v[198:201], v145
	ds_read_b128 v[202:205], v145 offset:1024
	ds_read_b128 v[206:209], v145 offset:2048
	ds_read_b128 v[210:213], v145 offset:3072
	ds_read_b128 v[214:217], v145 offset:4096
	ds_read_b128 v[218:221], v145 offset:5120
	ds_read_b128 v[222:225], v145 offset:6144
	ds_read_b128 v[226:229], v145 offset:7168
	global_load_lds_dwordx4 v[154:155], off
	s_add_i32 m0, s37, 0xe000
	v_lshl_add_u64 v[154:155], s[14:15], 0, v[138:139]
	global_load_lds_dwordx4 v[154:155], off
	s_setprio 0
	s_waitcnt vmcnt(8) lgkmcnt(0)
	s_barrier
	s_setprio 1
	v_mfma_f32_16x16x32_bf16 v[126:129], v[146:149], v[198:201], v[126:129]
	v_mfma_f32_16x16x32_bf16 v[122:125], v[162:165], v[198:201], v[122:125]
	v_mfma_f32_16x16x32_bf16 v[110:113], v[146:149], v[206:209], v[110:113]
	v_mfma_f32_16x16x32_bf16 v[106:109], v[162:165], v[206:209], v[106:109]
	v_mfma_f32_16x16x32_bf16 v[92:95], v[146:149], v[214:217], v[92:95]
	v_mfma_f32_16x16x32_bf16 v[88:91], v[162:165], v[214:217], v[88:91]
	v_mfma_f32_16x16x32_bf16 v[76:79], v[146:149], v[222:225], v[76:79]
	v_mfma_f32_16x16x32_bf16 v[72:75], v[162:165], v[222:225], v[72:75]
	v_mfma_f32_16x16x32_bf16 v[126:129], v[150:153], v[202:205], v[126:129]
	v_mfma_f32_16x16x32_bf16 v[122:125], v[166:169], v[202:205], v[122:125]
	v_mfma_f32_16x16x32_bf16 v[110:113], v[150:153], v[210:213], v[110:113]
	v_mfma_f32_16x16x32_bf16 v[106:109], v[166:169], v[210:213], v[106:109]
	v_mfma_f32_16x16x32_bf16 v[92:95], v[150:153], v[218:221], v[92:95]
	v_mfma_f32_16x16x32_bf16 v[88:91], v[166:169], v[218:221], v[88:91]
	v_mfma_f32_16x16x32_bf16 v[76:79], v[150:153], v[226:229], v[76:79]
	v_mfma_f32_16x16x32_bf16 v[72:75], v[166:169], v[226:229], v[72:75]
	s_setprio 0
	s_setprio 1
	v_mfma_f32_16x16x32_bf16 v[118:121], v[170:173], v[198:201], v[118:121]
	v_mfma_f32_16x16x32_bf16 v[114:117], v[190:193], v[198:201], v[114:117]
	v_mfma_f32_16x16x32_bf16 v[102:105], v[170:173], v[206:209], v[102:105]
	v_mfma_f32_16x16x32_bf16 v[98:101], v[190:193], v[206:209], v[98:101]
	v_mfma_f32_16x16x32_bf16 v[84:87], v[170:173], v[214:217], v[84:87]
	v_mfma_f32_16x16x32_bf16 v[80:83], v[190:193], v[214:217], v[80:83]
	v_mfma_f32_16x16x32_bf16 v[68:71], v[170:173], v[222:225], v[68:71]
	v_mfma_f32_16x16x32_bf16 v[64:67], v[190:193], v[222:225], v[64:67]
	v_mfma_f32_16x16x32_bf16 v[118:121], v[186:189], v[202:205], v[118:121]
	v_mfma_f32_16x16x32_bf16 v[114:117], v[194:197], v[202:205], v[114:117]
	v_mfma_f32_16x16x32_bf16 v[102:105], v[186:189], v[210:213], v[102:105]
	v_mfma_f32_16x16x32_bf16 v[98:101], v[194:197], v[210:213], v[98:101]
	v_mfma_f32_16x16x32_bf16 v[84:87], v[186:189], v[218:221], v[84:87]
	v_mfma_f32_16x16x32_bf16 v[80:83], v[194:197], v[218:221], v[80:83]
	v_mfma_f32_16x16x32_bf16 v[68:71], v[186:189], v[226:229], v[68:71]
	v_mfma_f32_16x16x32_bf16 v[64:67], v[194:197], v[226:229], v[64:67]
	s_setprio 0
	s_barrier
	s_setprio 2
	s_add_i32 s54, s54, s36
	v_lshl_add_u64 v[154:155], s[26:27], 0, v[96:97]
	s_mov_b32 m0, s54
	ds_read_b128 v[198:201], v145 offset:16384
	ds_read_b128 v[202:205], v145 offset:17408
	ds_read_b128 v[206:209], v145 offset:18432
	ds_read_b128 v[210:213], v145 offset:19456
	ds_read_b128 v[214:217], v145 offset:20480
	ds_read_b128 v[218:221], v145 offset:21504
	ds_read_b128 v[222:225], v145 offset:22528
	ds_read_b128 v[226:229], v145 offset:23552
	global_load_lds_dwordx4 v[154:155], off
	s_add_i32 m0, s54, 0x2000
	s_add_u32 s54, s26, 0x40000
	v_lshl_add_u64 v[156:157], s[26:27], 0, v[130:131]
	s_addc_u32 s55, s27, 0
	s_add_i32 s56, s56, s36
	global_load_lds_dwordx4 v[156:157], off
	v_lshl_add_u64 v[158:159], s[54:55], 0, v[96:97]
	s_mov_b32 m0, s56
	v_lshl_add_u64 v[182:183], s[28:29], 0, v[132:133]
	global_load_lds_dwordx4 v[158:159], off
	s_add_i32 m0, s56, 0x2000
	v_lshl_add_u64 v[158:159], s[54:55], 0, v[130:131]
	global_load_lds_dwordx4 v[158:159], off
	s_mov_b32 m0, s37
	v_lshl_add_u64 v[158:159], s[28:29], 0, v[134:135]
	global_load_lds_dwordx4 v[158:159], off
	s_mov_b32 m0, s38
	s_nop 0
	global_load_lds_dwordx4 v[182:183], off
	s_setprio 0
	s_waitcnt vmcnt(8) lgkmcnt(0)
	s_barrier
	s_setprio 1
	v_mfma_f32_16x16x32_bf16 v[60:63], v[146:149], v[198:201], v[60:63]
	v_mfma_f32_16x16x32_bf16 v[56:59], v[162:165], v[198:201], v[56:59]
	v_mfma_f32_16x16x32_bf16 v[44:47], v[146:149], v[206:209], v[44:47]
	v_mfma_f32_16x16x32_bf16 v[40:43], v[162:165], v[206:209], v[40:43]
	v_mfma_f32_16x16x32_bf16 v[28:31], v[146:149], v[214:217], v[28:31]
	v_mfma_f32_16x16x32_bf16 v[24:27], v[162:165], v[214:217], v[24:27]
	v_mfma_f32_16x16x32_bf16 v[12:15], v[146:149], v[222:225], v[12:15]
	v_mfma_f32_16x16x32_bf16 v[4:7], v[162:165], v[222:225], v[4:7]
	v_mfma_f32_16x16x32_bf16 v[60:63], v[150:153], v[202:205], v[60:63]
	v_mfma_f32_16x16x32_bf16 v[56:59], v[166:169], v[202:205], v[56:59]
	v_mfma_f32_16x16x32_bf16 v[44:47], v[150:153], v[210:213], v[44:47]
	v_mfma_f32_16x16x32_bf16 v[40:43], v[166:169], v[210:213], v[40:43]
	v_mfma_f32_16x16x32_bf16 v[28:31], v[150:153], v[218:221], v[28:31]
	v_mfma_f32_16x16x32_bf16 v[24:27], v[166:169], v[218:221], v[24:27]
	v_mfma_f32_16x16x32_bf16 v[12:15], v[150:153], v[226:229], v[12:15]
	v_mfma_f32_16x16x32_bf16 v[4:7], v[166:169], v[226:229], v[4:7]
	s_setprio 0
	s_setprio 1
	v_mfma_f32_16x16x32_bf16 v[52:55], v[170:173], v[198:201], v[52:55]
	v_mfma_f32_16x16x32_bf16 v[48:51], v[190:193], v[198:201], v[48:51]
	v_mfma_f32_16x16x32_bf16 v[36:39], v[170:173], v[206:209], v[36:39]
	v_mfma_f32_16x16x32_bf16 v[32:35], v[190:193], v[206:209], v[32:35]
	v_mfma_f32_16x16x32_bf16 v[20:23], v[170:173], v[214:217], v[20:23]
	v_mfma_f32_16x16x32_bf16 v[16:19], v[190:193], v[214:217], v[16:19]
	v_mfma_f32_16x16x32_bf16 v[8:11], v[170:173], v[222:225], v[8:11]
	v_mfma_f32_16x16x32_bf16 v[0:3], v[190:193], v[222:225], v[0:3]
	v_mfma_f32_16x16x32_bf16 v[52:55], v[186:189], v[202:205], v[52:55]
	v_mfma_f32_16x16x32_bf16 v[48:51], v[194:197], v[202:205], v[48:51]
	v_mfma_f32_16x16x32_bf16 v[36:39], v[186:189], v[210:213], v[36:39]
	v_mfma_f32_16x16x32_bf16 v[32:35], v[194:197], v[210:213], v[32:35]
	v_mfma_f32_16x16x32_bf16 v[20:23], v[186:189], v[218:221], v[20:23]
	v_mfma_f32_16x16x32_bf16 v[16:19], v[194:197], v[218:221], v[16:19]
	v_mfma_f32_16x16x32_bf16 v[8:11], v[186:189], v[226:229], v[8:11]
	v_mfma_f32_16x16x32_bf16 v[0:3], v[194:197], v[226:229], v[0:3]
	s_setprio 0
	s_barrier
	s_setprio 2
	s_add_i32 s54, 0, 0x18000
	s_add_i32 s55, 0, 0x1c000
	v_add_u32_e32 v166, s54, v141
	v_add_u32_e32 v184, s55, v141
	ds_read_b128 v[146:149], v166
	ds_read_b128 v[150:153], v166 offset:1024
	ds_read_b128 v[162:165], v166 offset:2048
	ds_read_b128 v[166:169], v166 offset:3072
	ds_read_b128 v[170:173], v184
	ds_read_b128 v[186:189], v184 offset:1024
	ds_read_b128 v[190:193], v184 offset:2048
	ds_read_b128 v[194:197], v184 offset:3072
	s_add_u32 s28, s28, 0x40000
	s_addc_u32 s29, s29, 0
	s_mov_b32 m0, s39
	v_lshl_add_u64 v[184:185], s[28:29], 0, v[134:135]
	ds_read_b128 v[198:201], v145 offset:32768
	ds_read_b128 v[202:205], v145 offset:33792
	ds_read_b128 v[206:209], v145 offset:34816
	ds_read_b128 v[210:213], v145 offset:35840
	ds_read_b128 v[214:217], v145 offset:36864
	ds_read_b128 v[218:221], v145 offset:37888
	ds_read_b128 v[222:225], v145 offset:38912
	ds_read_b128 v[226:229], v145 offset:39936
	global_load_lds_dwordx4 v[184:185], off
	s_mov_b32 m0, s40
	v_lshl_add_u64 v[184:185], s[28:29], 0, v[132:133]
	global_load_lds_dwordx4 v[184:185], off
	s_setprio 0
	s_waitcnt vmcnt(8) lgkmcnt(0)
	s_barrier
	s_setprio 1
	v_mfma_f32_16x16x32_bf16 v[126:129], v[146:149], v[198:201], v[126:129]
	v_mfma_f32_16x16x32_bf16 v[122:125], v[162:165], v[198:201], v[122:125]
	v_mfma_f32_16x16x32_bf16 v[110:113], v[146:149], v[206:209], v[110:113]
	v_mfma_f32_16x16x32_bf16 v[106:109], v[162:165], v[206:209], v[106:109]
	v_mfma_f32_16x16x32_bf16 v[92:95], v[146:149], v[214:217], v[92:95]
	v_mfma_f32_16x16x32_bf16 v[88:91], v[162:165], v[214:217], v[88:91]
	v_mfma_f32_16x16x32_bf16 v[76:79], v[146:149], v[222:225], v[76:79]
	v_mfma_f32_16x16x32_bf16 v[72:75], v[162:165], v[222:225], v[72:75]
	v_mfma_f32_16x16x32_bf16 v[126:129], v[150:153], v[202:205], v[126:129]
	v_mfma_f32_16x16x32_bf16 v[122:125], v[166:169], v[202:205], v[122:125]
	v_mfma_f32_16x16x32_bf16 v[110:113], v[150:153], v[210:213], v[110:113]
	v_mfma_f32_16x16x32_bf16 v[106:109], v[166:169], v[210:213], v[106:109]
	v_mfma_f32_16x16x32_bf16 v[92:95], v[150:153], v[218:221], v[92:95]
	v_mfma_f32_16x16x32_bf16 v[88:91], v[166:169], v[218:221], v[88:91]
	v_mfma_f32_16x16x32_bf16 v[76:79], v[150:153], v[226:229], v[76:79]
	v_mfma_f32_16x16x32_bf16 v[72:75], v[166:169], v[226:229], v[72:75]
	s_setprio 0
	s_setprio 1
	v_mfma_f32_16x16x32_bf16 v[118:121], v[170:173], v[198:201], v[118:121]
	v_mfma_f32_16x16x32_bf16 v[114:117], v[190:193], v[198:201], v[114:117]
	v_mfma_f32_16x16x32_bf16 v[102:105], v[170:173], v[206:209], v[102:105]
	v_mfma_f32_16x16x32_bf16 v[98:101], v[190:193], v[206:209], v[98:101]
	v_mfma_f32_16x16x32_bf16 v[84:87], v[170:173], v[214:217], v[84:87]
	v_mfma_f32_16x16x32_bf16 v[80:83], v[190:193], v[214:217], v[80:83]
	v_mfma_f32_16x16x32_bf16 v[68:71], v[170:173], v[222:225], v[68:71]
	v_mfma_f32_16x16x32_bf16 v[64:67], v[190:193], v[222:225], v[64:67]
	v_mfma_f32_16x16x32_bf16 v[118:121], v[186:189], v[202:205], v[118:121]
	v_mfma_f32_16x16x32_bf16 v[114:117], v[194:197], v[202:205], v[114:117]
	v_mfma_f32_16x16x32_bf16 v[102:105], v[186:189], v[210:213], v[102:105]
	v_mfma_f32_16x16x32_bf16 v[98:101], v[194:197], v[210:213], v[98:101]
	v_mfma_f32_16x16x32_bf16 v[84:87], v[186:189], v[218:221], v[84:87]
	v_mfma_f32_16x16x32_bf16 v[80:83], v[194:197], v[218:221], v[80:83]
	v_mfma_f32_16x16x32_bf16 v[68:71], v[186:189], v[226:229], v[68:71]
	v_mfma_f32_16x16x32_bf16 v[64:67], v[194:197], v[226:229], v[64:67]
	s_setprio 0
	s_barrier
	s_setprio 2
	s_add_i32 s28, s54, s36
	v_lshl_add_u64 v[154:155], v[154:155], 0, s[16:17]
	s_mov_b32 m0, s28
	ds_read_b128 v[198:201], v145 offset:49152
	ds_read_b128 v[202:205], v145 offset:50176
	ds_read_b128 v[206:209], v145 offset:51200
	ds_read_b128 v[210:213], v145 offset:52224
	ds_read_b128 v[214:217], v145 offset:53248
	ds_read_b128 v[218:221], v145 offset:54272
	ds_read_b128 v[222:225], v145 offset:55296
	ds_read_b128 v[226:229], v145 offset:56320
	global_load_lds_dwordx4 v[154:155], off
	s_add_i32 m0, s28, 0x2000
	s_add_u32 s26, s26, 0x40080
	v_lshl_add_u64 v[154:155], v[156:157], 0, s[16:17]
	s_addc_u32 s27, s27, 0
	s_add_i32 s28, s55, s36
	global_load_lds_dwordx4 v[154:155], off
	s_mov_b32 m0, s28
	v_lshl_add_u64 v[154:155], s[26:27], 0, v[96:97]
	global_load_lds_dwordx4 v[154:155], off
	s_add_i32 m0, s28, 0x2000
	v_lshl_add_u64 v[154:155], s[26:27], 0, v[130:131]
	global_load_lds_dwordx4 v[154:155], off
	s_mov_b32 m0, s41
	v_lshl_add_u64 v[154:155], v[158:159], 0, s[16:17]
	global_load_lds_dwordx4 v[154:155], off
	s_mov_b32 m0, s42
	v_lshl_add_u64 v[154:155], v[182:183], 0, s[16:17]
	global_load_lds_dwordx4 v[154:155], off
	s_setprio 0
	s_waitcnt vmcnt(8) lgkmcnt(0)
	s_barrier
	s_setprio 1
	v_mfma_f32_16x16x32_bf16 v[60:63], v[146:149], v[198:201], v[60:63]
	v_mfma_f32_16x16x32_bf16 v[56:59], v[162:165], v[198:201], v[56:59]
	v_mfma_f32_16x16x32_bf16 v[44:47], v[146:149], v[206:209], v[44:47]
	v_mfma_f32_16x16x32_bf16 v[40:43], v[162:165], v[206:209], v[40:43]
	v_mfma_f32_16x16x32_bf16 v[28:31], v[146:149], v[214:217], v[28:31]
	v_mfma_f32_16x16x32_bf16 v[24:27], v[162:165], v[214:217], v[24:27]
	v_mfma_f32_16x16x32_bf16 v[12:15], v[146:149], v[222:225], v[12:15]
	v_mfma_f32_16x16x32_bf16 v[4:7], v[162:165], v[222:225], v[4:7]
	v_mfma_f32_16x16x32_bf16 v[60:63], v[150:153], v[202:205], v[60:63]
	v_mfma_f32_16x16x32_bf16 v[56:59], v[166:169], v[202:205], v[56:59]
	v_mfma_f32_16x16x32_bf16 v[44:47], v[150:153], v[210:213], v[44:47]
	v_mfma_f32_16x16x32_bf16 v[40:43], v[166:169], v[210:213], v[40:43]
	v_mfma_f32_16x16x32_bf16 v[28:31], v[150:153], v[218:221], v[28:31]
	v_mfma_f32_16x16x32_bf16 v[24:27], v[166:169], v[218:221], v[24:27]
	v_mfma_f32_16x16x32_bf16 v[12:15], v[150:153], v[226:229], v[12:15]
	v_mfma_f32_16x16x32_bf16 v[4:7], v[166:169], v[226:229], v[4:7]
	s_setprio 0
	s_setprio 1
	v_mfma_f32_16x16x32_bf16 v[52:55], v[170:173], v[198:201], v[52:55]
	v_mfma_f32_16x16x32_bf16 v[48:51], v[190:193], v[198:201], v[48:51]
	v_mfma_f32_16x16x32_bf16 v[36:39], v[170:173], v[206:209], v[36:39]
	v_mfma_f32_16x16x32_bf16 v[32:35], v[190:193], v[206:209], v[32:35]
	v_mfma_f32_16x16x32_bf16 v[20:23], v[170:173], v[214:217], v[20:23]
	v_mfma_f32_16x16x32_bf16 v[16:19], v[190:193], v[214:217], v[16:19]
	v_mfma_f32_16x16x32_bf16 v[8:11], v[170:173], v[222:225], v[8:11]
	v_mfma_f32_16x16x32_bf16 v[0:3], v[190:193], v[222:225], v[0:3]
	v_mfma_f32_16x16x32_bf16 v[52:55], v[186:189], v[202:205], v[52:55]
	v_mfma_f32_16x16x32_bf16 v[48:51], v[194:197], v[202:205], v[48:51]
	v_mfma_f32_16x16x32_bf16 v[36:39], v[186:189], v[210:213], v[36:39]
	v_mfma_f32_16x16x32_bf16 v[32:35], v[194:197], v[210:213], v[32:35]
	v_mfma_f32_16x16x32_bf16 v[20:23], v[186:189], v[218:221], v[20:23]
	v_mfma_f32_16x16x32_bf16 v[16:19], v[194:197], v[218:221], v[16:19]
	v_mfma_f32_16x16x32_bf16 v[8:11], v[186:189], v[226:229], v[8:11]
	v_mfma_f32_16x16x32_bf16 v[0:3], v[194:197], v[226:229], v[0:3]
	s_setprio 0
	s_barrier
	s_setprio 2
	s_add_i32 s53, s53, 2
	s_add_u32 s14, s14, 0x100
	s_addc_u32 s15, s15, 0
	s_add_u32 s51, s51, 0x100
	s_addc_u32 s52, s52, 0
	s_cmp_gt_u32 s53, 13
	s_cbranch_scc0 .LBB0_271
	s_and_b64 vcc, exec, s[12:13]
	s_cbranch_vccz .LBB0_274
	s_barrier

.LBB0_361:
	s_add_u32 s34, s30, 0xfffc0080
	s_addc_u32 s35, s31, -1
	s_add_i32 s62, 0, 0x10000
	s_cmp_eq_u32 s61, 12
	s_cselect_b32 s37, s25, s35
	s_cselect_b32 s36, s57, s34
	v_add_u32_e32 v96, s62, v151
	s_cselect_b32 s35, s15, s60
	s_cselect_b32 s34, s58, s59
	s_add_i32 s64, 0, 0x14000
	ds_read_b128 v[164:167], v96
	ds_read_b128 v[168:171], v96 offset:1024
	ds_read_b128 v[186:189], v96 offset:2048
	ds_read_b128 v[190:193], v96 offset:3072
	v_add_u32_e32 v96, s64, v151
	ds_read_b128 v[194:197], v96
	ds_read_b128 v[198:201], v96 offset:1024
	ds_read_b128 v[202:205], v96 offset:2048
	ds_read_b128 v[206:209], v96 offset:3072
	v_lshl_add_u64 v[154:155], s[30:31], 0, v[146:147]
	s_add_i32 m0, s43, 0xc000
	ds_read_b128 v[210:213], v162
	ds_read_b128 v[214:217], v162 offset:1024
	ds_read_b128 v[218:221], v162 offset:2048
	ds_read_b128 v[222:225], v162 offset:3072
	ds_read_b128 v[226:229], v162 offset:4096
	ds_read_b128 v[230:233], v162 offset:5120
	ds_read_b128 v[242:245], v162 offset:6144
	ds_read_b128 v[246:249], v162 offset:7168
	global_load_lds_dwordx4 v[154:155], off
	s_add_i32 m0, s43, 0xe000
	v_lshl_add_u64 v[154:155], s[30:31], 0, v[148:149]
	global_load_lds_dwordx4 v[154:155], off
	s_setprio 0
	s_waitcnt vmcnt(8) lgkmcnt(0)
	s_barrier
	s_setprio 1
	v_mfma_f32_16x16x32_bf16 v[126:129], v[164:167], v[210:213], v[126:129]
	v_mfma_f32_16x16x32_bf16 v[122:125], v[186:189], v[210:213], v[122:125]
	v_mfma_f32_16x16x32_bf16 v[118:121], v[164:167], v[218:221], v[118:121]
	v_mfma_f32_16x16x32_bf16 v[114:117], v[186:189], v[218:221], v[114:117]
	v_mfma_f32_16x16x32_bf16 v[110:113], v[164:167], v[226:229], v[110:113]
	v_mfma_f32_16x16x32_bf16 v[106:109], v[186:189], v[226:229], v[106:109]
	v_mfma_f32_16x16x32_bf16 v[102:105], v[164:167], v[242:245], v[102:105]
	v_mfma_f32_16x16x32_bf16 v[98:101], v[186:189], v[242:245], v[98:101]
	v_mfma_f32_16x16x32_bf16 v[126:129], v[168:171], v[214:217], v[126:129]
	v_mfma_f32_16x16x32_bf16 v[122:125], v[190:193], v[214:217], v[122:125]
	v_mfma_f32_16x16x32_bf16 v[118:121], v[168:171], v[222:225], v[118:121]
	v_mfma_f32_16x16x32_bf16 v[114:117], v[190:193], v[222:225], v[114:117]
	v_mfma_f32_16x16x32_bf16 v[110:113], v[168:171], v[230:233], v[110:113]
	v_mfma_f32_16x16x32_bf16 v[106:109], v[190:193], v[230:233], v[106:109]
	v_mfma_f32_16x16x32_bf16 v[102:105], v[168:171], v[246:249], v[102:105]
	v_mfma_f32_16x16x32_bf16 v[98:101], v[190:193], v[246:249], v[98:101]
	s_setprio 0
	s_setprio 1
	v_mfma_f32_16x16x32_bf16 v[76:79], v[194:197], v[210:213], v[76:79]
	v_mfma_f32_16x16x32_bf16 v[64:67], v[202:205], v[210:213], v[64:67]
	v_mfma_f32_16x16x32_bf16 v[60:63], v[194:197], v[218:221], v[60:63]
	v_mfma_f32_16x16x32_bf16 v[52:55], v[202:205], v[218:221], v[52:55]
	v_mfma_f32_16x16x32_bf16 v[44:47], v[194:197], v[226:229], v[44:47]
	v_mfma_f32_16x16x32_bf16 v[40:43], v[202:205], v[226:229], v[40:43]
	v_mfma_f32_16x16x32_bf16 v[36:39], v[194:197], v[242:245], v[36:39]
	v_mfma_f32_16x16x32_bf16 v[32:35], v[202:205], v[242:245], v[32:35]
	v_mfma_f32_16x16x32_bf16 v[76:79], v[198:201], v[214:217], v[76:79]
	v_mfma_f32_16x16x32_bf16 v[64:67], v[206:209], v[214:217], v[64:67]
	v_mfma_f32_16x16x32_bf16 v[60:63], v[198:201], v[222:225], v[60:63]
	v_mfma_f32_16x16x32_bf16 v[52:55], v[206:209], v[222:225], v[52:55]
	v_mfma_f32_16x16x32_bf16 v[44:47], v[198:201], v[230:233], v[44:47]
	v_mfma_f32_16x16x32_bf16 v[40:43], v[206:209], v[230:233], v[40:43]
	v_mfma_f32_16x16x32_bf16 v[36:39], v[198:201], v[246:249], v[36:39]
	v_mfma_f32_16x16x32_bf16 v[32:35], v[206:209], v[246:249], v[32:35]
	s_setprio 0
	s_barrier
	s_setprio 2
	s_add_i32 s62, s62, s40
	v_lshl_add_u64 v[154:155], s[34:35], 0, v[134:135]
	s_mov_b32 m0, s62
	ds_read_b128 v[210:213], v162 offset:16384
	ds_read_b128 v[214:217], v162 offset:17408
	ds_read_b128 v[218:221], v162 offset:18432
	ds_read_b128 v[222:225], v162 offset:19456
	ds_read_b128 v[226:229], v162 offset:20480
	ds_read_b128 v[230:233], v162 offset:21504
	ds_read_b128 v[242:245], v162 offset:22528
	ds_read_b128 v[246:249], v162 offset:23552
	global_load_lds_dwordx4 v[154:155], off
	s_add_i32 m0, s62, 0x2000
	s_add_u32 s62, s34, 0x40000
	v_lshl_add_u64 v[156:157], s[34:35], 0, v[130:131]
	s_addc_u32 s63, s35, 0
	s_add_i32 s64, s64, s40
	global_load_lds_dwordx4 v[156:157], off
	v_lshl_add_u64 v[158:159], s[62:63], 0, v[134:135]
	s_mov_b32 m0, s64
	v_lshl_add_u64 v[172:173], s[36:37], 0, v[132:133]
	global_load_lds_dwordx4 v[158:159], off
	s_add_i32 m0, s64, 0x2000
	v_lshl_add_u64 v[158:159], s[62:63], 0, v[130:131]
	global_load_lds_dwordx4 v[158:159], off
	s_mov_b32 m0, s43
	v_lshl_add_u64 v[158:159], s[36:37], 0, v[136:137]
	global_load_lds_dwordx4 v[158:159], off
	s_mov_b32 m0, s44
	s_nop 0
	global_load_lds_dwordx4 v[172:173], off
	s_setprio 0
	s_waitcnt vmcnt(8) lgkmcnt(0)
	s_barrier
	s_setprio 1
	v_mfma_f32_16x16x32_bf16 v[92:95], v[164:167], v[210:213], v[92:95]
	v_mfma_f32_16x16x32_bf16 v[88:91], v[186:189], v[210:213], v[88:91]
	v_mfma_f32_16x16x32_bf16 v[84:87], v[164:167], v[218:221], v[84:87]
	v_mfma_f32_16x16x32_bf16 v[80:83], v[186:189], v[218:221], v[80:83]
	v_mfma_f32_16x16x32_bf16 v[72:75], v[164:167], v[226:229], v[72:75]
	v_mfma_f32_16x16x32_bf16 v[68:71], v[186:189], v[226:229], v[68:71]
	v_mfma_f32_16x16x32_bf16 v[56:59], v[164:167], v[242:245], v[56:59]
	v_mfma_f32_16x16x32_bf16 v[48:51], v[186:189], v[242:245], v[48:51]
	v_mfma_f32_16x16x32_bf16 v[92:95], v[168:171], v[214:217], v[92:95]
	v_mfma_f32_16x16x32_bf16 v[88:91], v[190:193], v[214:217], v[88:91]
	v_mfma_f32_16x16x32_bf16 v[84:87], v[168:171], v[222:225], v[84:87]
	v_mfma_f32_16x16x32_bf16 v[80:83], v[190:193], v[222:225], v[80:83]
	v_mfma_f32_16x16x32_bf16 v[72:75], v[168:171], v[230:233], v[72:75]
	v_mfma_f32_16x16x32_bf16 v[68:71], v[190:193], v[230:233], v[68:71]
	v_mfma_f32_16x16x32_bf16 v[56:59], v[168:171], v[246:249], v[56:59]
	v_mfma_f32_16x16x32_bf16 v[48:51], v[190:193], v[246:249], v[48:51]
	s_setprio 0
	s_setprio 1
	v_mfma_f32_16x16x32_bf16 v[28:31], v[194:197], v[210:213], v[28:31]
	v_mfma_f32_16x16x32_bf16 v[24:27], v[202:205], v[210:213], v[24:27]
	v_mfma_f32_16x16x32_bf16 v[20:23], v[194:197], v[218:221], v[20:23]
	v_mfma_f32_16x16x32_bf16 v[16:19], v[202:205], v[218:221], v[16:19]
	v_mfma_f32_16x16x32_bf16 v[12:15], v[194:197], v[226:229], v[12:15]
	v_mfma_f32_16x16x32_bf16 v[8:11], v[202:205], v[226:229], v[8:11]
	v_mfma_f32_16x16x32_bf16 v[4:7], v[194:197], v[242:245], v[4:7]
	v_mfma_f32_16x16x32_bf16 v[0:3], v[202:205], v[242:245], v[0:3]
	v_mfma_f32_16x16x32_bf16 v[28:31], v[198:201], v[214:217], v[28:31]
	v_mfma_f32_16x16x32_bf16 v[24:27], v[206:209], v[214:217], v[24:27]
	v_mfma_f32_16x16x32_bf16 v[20:23], v[198:201], v[222:225], v[20:23]
	v_mfma_f32_16x16x32_bf16 v[16:19], v[206:209], v[222:225], v[16:19]
	v_mfma_f32_16x16x32_bf16 v[12:15], v[198:201], v[230:233], v[12:15]
	v_mfma_f32_16x16x32_bf16 v[8:11], v[206:209], v[230:233], v[8:11]
	v_mfma_f32_16x16x32_bf16 v[4:7], v[198:201], v[246:249], v[4:7]
	v_mfma_f32_16x16x32_bf16 v[0:3], v[206:209], v[246:249], v[0:3]
	s_setprio 0
	s_barrier
	s_setprio 2
	s_add_i32 s62, 0, 0x18000
	v_add_u32_e32 v96, s62, v151
	s_add_i32 s63, 0, 0x1c000
	ds_read_b128 v[164:167], v96
	ds_read_b128 v[168:171], v96 offset:1024
	ds_read_b128 v[186:189], v96 offset:2048
	ds_read_b128 v[190:193], v96 offset:3072
	v_add_u32_e32 v96, s63, v151
	ds_read_b128 v[194:197], v96
	ds_read_b128 v[198:201], v96 offset:1024
	ds_read_b128 v[202:205], v96 offset:2048
	ds_read_b128 v[206:209], v96 offset:3072
	s_add_u32 s36, s36, 0x40000
	s_addc_u32 s37, s37, 0
	s_mov_b32 m0, s45
	v_lshl_add_u64 v[182:183], s[36:37], 0, v[136:137]
	ds_read_b128 v[210:213], v162 offset:32768
	ds_read_b128 v[214:217], v162 offset:33792
	ds_read_b128 v[218:221], v162 offset:34816
	ds_read_b128 v[222:225], v162 offset:35840
	ds_read_b128 v[226:229], v162 offset:36864
	ds_read_b128 v[230:233], v162 offset:37888
	ds_read_b128 v[242:245], v162 offset:38912
	ds_read_b128 v[246:249], v162 offset:39936
	global_load_lds_dwordx4 v[182:183], off
	s_mov_b32 m0, s46
	v_lshl_add_u64 v[182:183], s[36:37], 0, v[132:133]
	global_load_lds_dwordx4 v[182:183], off
	s_setprio 0
	s_waitcnt vmcnt(8) lgkmcnt(0)
	s_barrier
	s_setprio 1
	v_mfma_f32_16x16x32_bf16 v[126:129], v[164:167], v[210:213], v[126:129]
	v_mfma_f32_16x16x32_bf16 v[122:125], v[186:189], v[210:213], v[122:125]
	v_mfma_f32_16x16x32_bf16 v[118:121], v[164:167], v[218:221], v[118:121]
	v_mfma_f32_16x16x32_bf16 v[114:117], v[186:189], v[218:221], v[114:117]
	v_mfma_f32_16x16x32_bf16 v[110:113], v[164:167], v[226:229], v[110:113]
	v_mfma_f32_16x16x32_bf16 v[106:109], v[186:189], v[226:229], v[106:109]
	v_mfma_f32_16x16x32_bf16 v[102:105], v[164:167], v[242:245], v[102:105]
	v_mfma_f32_16x16x32_bf16 v[98:101], v[186:189], v[242:245], v[98:101]
	v_mfma_f32_16x16x32_bf16 v[126:129], v[168:171], v[214:217], v[126:129]
	v_mfma_f32_16x16x32_bf16 v[122:125], v[190:193], v[214:217], v[122:125]
	v_mfma_f32_16x16x32_bf16 v[118:121], v[168:171], v[222:225], v[118:121]
	v_mfma_f32_16x16x32_bf16 v[114:117], v[190:193], v[222:225], v[114:117]
	v_mfma_f32_16x16x32_bf16 v[110:113], v[168:171], v[230:233], v[110:113]
	v_mfma_f32_16x16x32_bf16 v[106:109], v[190:193], v[230:233], v[106:109]
	v_mfma_f32_16x16x32_bf16 v[102:105], v[168:171], v[246:249], v[102:105]
	v_mfma_f32_16x16x32_bf16 v[98:101], v[190:193], v[246:249], v[98:101]
	s_setprio 0
	s_setprio 1
	v_mfma_f32_16x16x32_bf16 v[76:79], v[194:197], v[210:213], v[76:79]
	v_mfma_f32_16x16x32_bf16 v[64:67], v[202:205], v[210:213], v[64:67]
	v_mfma_f32_16x16x32_bf16 v[60:63], v[194:197], v[218:221], v[60:63]
	v_mfma_f32_16x16x32_bf16 v[52:55], v[202:205], v[218:221], v[52:55]
	v_mfma_f32_16x16x32_bf16 v[44:47], v[194:197], v[226:229], v[44:47]
	v_mfma_f32_16x16x32_bf16 v[40:43], v[202:205], v[226:229], v[40:43]
	v_mfma_f32_16x16x32_bf16 v[36:39], v[194:197], v[242:245], v[36:39]
	v_mfma_f32_16x16x32_bf16 v[32:35], v[202:205], v[242:245], v[32:35]
	v_mfma_f32_16x16x32_bf16 v[76:79], v[198:201], v[214:217], v[76:79]
	v_mfma_f32_16x16x32_bf16 v[64:67], v[206:209], v[214:217], v[64:67]
	v_mfma_f32_16x16x32_bf16 v[60:63], v[198:201], v[222:225], v[60:63]
	v_mfma_f32_16x16x32_bf16 v[52:55], v[206:209], v[222:225], v[52:55]
	v_mfma_f32_16x16x32_bf16 v[44:47], v[198:201], v[230:233], v[44:47]
	v_mfma_f32_16x16x32_bf16 v[40:43], v[206:209], v[230:233], v[40:43]
	v_mfma_f32_16x16x32_bf16 v[36:39], v[198:201], v[246:249], v[36:39]
	v_mfma_f32_16x16x32_bf16 v[32:35], v[206:209], v[246:249], v[32:35]
	s_setprio 0
	s_barrier
	s_setprio 2
	s_add_i32 s36, s62, s40
	v_lshl_add_u64 v[154:155], v[154:155], 0, s[16:17]
	s_mov_b32 m0, s36
	ds_read_b128 v[210:213], v162 offset:49152
	ds_read_b128 v[214:217], v162 offset:50176
	ds_read_b128 v[218:221], v162 offset:51200
	ds_read_b128 v[222:225], v162 offset:52224
	ds_read_b128 v[226:229], v162 offset:53248
	ds_read_b128 v[230:233], v162 offset:54272
	ds_read_b128 v[242:245], v162 offset:55296
	ds_read_b128 v[246:249], v162 offset:56320
	global_load_lds_dwordx4 v[154:155], off
	s_add_i32 m0, s36, 0x2000
	s_add_u32 s34, s34, 0x40080
	v_lshl_add_u64 v[154:155], v[156:157], 0, s[16:17]
	s_addc_u32 s35, s35, 0
	s_add_i32 s36, s63, s40
	global_load_lds_dwordx4 v[154:155], off
	s_mov_b32 m0, s36
	v_lshl_add_u64 v[154:155], s[34:35], 0, v[134:135]
	global_load_lds_dwordx4 v[154:155], off
	s_add_i32 m0, s36, 0x2000
	v_lshl_add_u64 v[154:155], s[34:35], 0, v[130:131]
	global_load_lds_dwordx4 v[154:155], off
	s_mov_b32 m0, s50
	v_lshl_add_u64 v[154:155], v[158:159], 0, s[16:17]
	global_load_lds_dwordx4 v[154:155], off
	s_mov_b32 m0, s51
	v_lshl_add_u64 v[154:155], v[172:173], 0, s[16:17]
	global_load_lds_dwordx4 v[154:155], off
	s_setprio 0
	s_waitcnt vmcnt(8) lgkmcnt(0)
	s_barrier
	s_setprio 1
	v_mfma_f32_16x16x32_bf16 v[92:95], v[164:167], v[210:213], v[92:95]
	v_mfma_f32_16x16x32_bf16 v[88:91], v[186:189], v[210:213], v[88:91]
	v_mfma_f32_16x16x32_bf16 v[84:87], v[164:167], v[218:221], v[84:87]
	v_mfma_f32_16x16x32_bf16 v[80:83], v[186:189], v[218:221], v[80:83]
	v_mfma_f32_16x16x32_bf16 v[72:75], v[164:167], v[226:229], v[72:75]
	v_mfma_f32_16x16x32_bf16 v[68:71], v[186:189], v[226:229], v[68:71]
	v_mfma_f32_16x16x32_bf16 v[56:59], v[164:167], v[242:245], v[56:59]
	v_mfma_f32_16x16x32_bf16 v[48:51], v[186:189], v[242:245], v[48:51]
	v_mfma_f32_16x16x32_bf16 v[92:95], v[168:171], v[214:217], v[92:95]
	v_mfma_f32_16x16x32_bf16 v[88:91], v[190:193], v[214:217], v[88:91]
	v_mfma_f32_16x16x32_bf16 v[84:87], v[168:171], v[222:225], v[84:87]
	v_mfma_f32_16x16x32_bf16 v[80:83], v[190:193], v[222:225], v[80:83]
	v_mfma_f32_16x16x32_bf16 v[72:75], v[168:171], v[230:233], v[72:75]
	v_mfma_f32_16x16x32_bf16 v[68:71], v[190:193], v[230:233], v[68:71]
	v_mfma_f32_16x16x32_bf16 v[56:59], v[168:171], v[246:249], v[56:59]
	v_mfma_f32_16x16x32_bf16 v[48:51], v[190:193], v[246:249], v[48:51]
	s_setprio 0
	s_setprio 1
	v_mfma_f32_16x16x32_bf16 v[28:31], v[194:197], v[210:213], v[28:31]
	v_mfma_f32_16x16x32_bf16 v[24:27], v[202:205], v[210:213], v[24:27]
	v_mfma_f32_16x16x32_bf16 v[20:23], v[194:197], v[218:221], v[20:23]
	v_mfma_f32_16x16x32_bf16 v[16:19], v[202:205], v[218:221], v[16:19]
	v_mfma_f32_16x16x32_bf16 v[12:15], v[194:197], v[226:229], v[12:15]
	v_mfma_f32_16x16x32_bf16 v[8:11], v[202:205], v[226:229], v[8:11]
	v_mfma_f32_16x16x32_bf16 v[4:7], v[194:197], v[242:245], v[4:7]
	v_mfma_f32_16x16x32_bf16 v[0:3], v[202:205], v[242:245], v[0:3]
	v_mfma_f32_16x16x32_bf16 v[28:31], v[198:201], v[214:217], v[28:31]
	v_mfma_f32_16x16x32_bf16 v[24:27], v[206:209], v[214:217], v[24:27]
	v_mfma_f32_16x16x32_bf16 v[20:23], v[198:201], v[222:225], v[20:23]
	v_mfma_f32_16x16x32_bf16 v[16:19], v[206:209], v[222:225], v[16:19]
	v_mfma_f32_16x16x32_bf16 v[12:15], v[198:201], v[230:233], v[12:15]
	v_mfma_f32_16x16x32_bf16 v[8:11], v[206:209], v[230:233], v[8:11]
	v_mfma_f32_16x16x32_bf16 v[4:7], v[198:201], v[246:249], v[4:7]
	v_mfma_f32_16x16x32_bf16 v[0:3], v[206:209], v[246:249], v[0:3]
	s_setprio 0
	s_barrier
	s_setprio 2
	s_add_i32 s61, s61, 2
	s_add_u32 s30, s30, 0x100
	s_addc_u32 s31, s31, 0
	s_add_u32 s59, s59, 0x100
	s_addc_u32 s60, s60, 0
	s_cmp_gt_u32 s61, 13
	s_cbranch_scc0 .LBB0_361
	s_and_b64 vcc, exec, s[20:21]
	s_cbranch_vccz .LBB0_364
	s_barrier

.LBB0_393:
	s_add_u32 s26, s14, 0xfffc0080
	s_addc_u32 s27, s15, -1
	s_add_i32 s57, 0, 0x10000
	s_cmp_eq_u32 s56, 12
	s_cselect_b32 s29, s19, s27
	s_cselect_b32 s28, s52, s26
	v_add_u32_e32 v151, s57, v141
	s_cselect_b32 s27, s5, s55
	s_cselect_b32 s26, s53, s54
	s_add_i32 s60, 0, 0x14000
	ds_read_b128 v[162:165], v151
	ds_read_b128 v[166:169], v151 offset:1024
	ds_read_b128 v[170:173], v151 offset:2048
	ds_read_b128 v[186:189], v151 offset:3072
	v_add_u32_e32 v151, s60, v141
	ds_read_b128 v[190:193], v151
	ds_read_b128 v[194:197], v151 offset:1024
	ds_read_b128 v[198:201], v151 offset:2048
	ds_read_b128 v[202:205], v151 offset:3072
	v_lshl_add_u64 v[152:153], s[14:15], 0, v[146:147]
	s_add_i32 m0, s39, 0xc000
	ds_read_b128 v[206:209], v150
	ds_read_b128 v[210:213], v150 offset:1024
	ds_read_b128 v[214:217], v150 offset:2048
	ds_read_b128 v[218:221], v150 offset:3072
	ds_read_b128 v[222:225], v150 offset:4096
	ds_read_b128 v[226:229], v150 offset:5120
	ds_read_b128 v[230:233], v150 offset:6144
	ds_read_b128 v[242:245], v150 offset:7168
	global_load_lds_dwordx4 v[152:153], off
	s_add_i32 m0, s39, 0xe000
	v_lshl_add_u64 v[152:153], s[14:15], 0, v[148:149]
	global_load_lds_dwordx4 v[152:153], off
	s_setprio 0
	s_waitcnt vmcnt(8) lgkmcnt(0)
	s_barrier
	s_setprio 1
	v_mfma_f32_16x16x32_bf16 v[126:129], v[162:165], v[206:209], v[126:129]
	v_mfma_f32_16x16x32_bf16 v[122:125], v[170:173], v[206:209], v[122:125]
	v_mfma_f32_16x16x32_bf16 v[118:121], v[162:165], v[214:217], v[118:121]
	v_mfma_f32_16x16x32_bf16 v[114:117], v[170:173], v[214:217], v[114:117]
	v_mfma_f32_16x16x32_bf16 v[110:113], v[162:165], v[222:225], v[110:113]
	v_mfma_f32_16x16x32_bf16 v[106:109], v[170:173], v[222:225], v[106:109]
	v_mfma_f32_16x16x32_bf16 v[102:105], v[162:165], v[230:233], v[102:105]
	v_mfma_f32_16x16x32_bf16 v[98:101], v[170:173], v[230:233], v[98:101]
	v_mfma_f32_16x16x32_bf16 v[126:129], v[166:169], v[210:213], v[126:129]
	v_mfma_f32_16x16x32_bf16 v[122:125], v[186:189], v[210:213], v[122:125]
	v_mfma_f32_16x16x32_bf16 v[118:121], v[166:169], v[218:221], v[118:121]
	v_mfma_f32_16x16x32_bf16 v[114:117], v[186:189], v[218:221], v[114:117]
	v_mfma_f32_16x16x32_bf16 v[110:113], v[166:169], v[226:229], v[110:113]
	v_mfma_f32_16x16x32_bf16 v[106:109], v[186:189], v[226:229], v[106:109]
	v_mfma_f32_16x16x32_bf16 v[102:105], v[166:169], v[242:245], v[102:105]
	v_mfma_f32_16x16x32_bf16 v[98:101], v[186:189], v[242:245], v[98:101]
	s_setprio 0
	s_setprio 1
	v_mfma_f32_16x16x32_bf16 v[68:71], v[190:193], v[206:209], v[68:71]
	v_mfma_f32_16x16x32_bf16 v[64:67], v[198:201], v[206:209], v[64:67]
	v_mfma_f32_16x16x32_bf16 v[52:55], v[190:193], v[214:217], v[52:55]
	v_mfma_f32_16x16x32_bf16 v[48:51], v[198:201], v[214:217], v[48:51]
	v_mfma_f32_16x16x32_bf16 v[44:47], v[190:193], v[222:225], v[44:47]
	v_mfma_f32_16x16x32_bf16 v[40:43], v[198:201], v[222:225], v[40:43]
	v_mfma_f32_16x16x32_bf16 v[36:39], v[190:193], v[230:233], v[36:39]
	v_mfma_f32_16x16x32_bf16 v[32:35], v[198:201], v[230:233], v[32:35]
	v_mfma_f32_16x16x32_bf16 v[68:71], v[194:197], v[210:213], v[68:71]
	v_mfma_f32_16x16x32_bf16 v[64:67], v[202:205], v[210:213], v[64:67]
	v_mfma_f32_16x16x32_bf16 v[52:55], v[194:197], v[218:221], v[52:55]
	v_mfma_f32_16x16x32_bf16 v[48:51], v[202:205], v[218:221], v[48:51]
	v_mfma_f32_16x16x32_bf16 v[44:47], v[194:197], v[226:229], v[44:47]
	v_mfma_f32_16x16x32_bf16 v[40:43], v[202:205], v[226:229], v[40:43]
	v_mfma_f32_16x16x32_bf16 v[36:39], v[194:197], v[242:245], v[36:39]
	v_mfma_f32_16x16x32_bf16 v[32:35], v[202:205], v[242:245], v[32:35]
	s_setprio 0
	s_barrier
	s_setprio 2
	s_add_i32 s57, s57, s36
	v_lshl_add_u64 v[152:153], s[26:27], 0, v[96:97]
	s_mov_b32 m0, s57
	ds_read_b128 v[206:209], v150 offset:16384
	ds_read_b128 v[210:213], v150 offset:17408
	ds_read_b128 v[214:217], v150 offset:18432
	ds_read_b128 v[218:221], v150 offset:19456
	ds_read_b128 v[222:225], v150 offset:20480
	ds_read_b128 v[226:229], v150 offset:21504
	ds_read_b128 v[230:233], v150 offset:22528
	ds_read_b128 v[242:245], v150 offset:23552
	global_load_lds_dwordx4 v[152:153], off
	s_add_i32 m0, s57, 0x2000
	s_add_u32 s58, s26, 0x40000
	v_lshl_add_u64 v[154:155], s[26:27], 0, v[130:131]
	s_addc_u32 s59, s27, 0
	s_add_i32 s57, s60, s36
	global_load_lds_dwordx4 v[154:155], off
	v_lshl_add_u64 v[156:157], s[58:59], 0, v[96:97]
	s_mov_b32 m0, s57
	v_lshl_add_u64 v[158:159], s[28:29], 0, v[132:133]
	global_load_lds_dwordx4 v[156:157], off
	s_add_i32 m0, s57, 0x2000
	v_lshl_add_u64 v[156:157], s[58:59], 0, v[130:131]
	global_load_lds_dwordx4 v[156:157], off
	s_mov_b32 m0, s39
	v_lshl_add_u64 v[156:157], s[28:29], 0, v[134:135]
	global_load_lds_dwordx4 v[156:157], off
	s_mov_b32 m0, s40
	s_nop 0
	global_load_lds_dwordx4 v[158:159], off
	s_setprio 0
	s_waitcnt vmcnt(8) lgkmcnt(0)
	s_barrier
	s_setprio 1
	v_mfma_f32_16x16x32_bf16 v[92:95], v[162:165], v[206:209], v[92:95]
	v_mfma_f32_16x16x32_bf16 v[88:91], v[170:173], v[206:209], v[88:91]
	v_mfma_f32_16x16x32_bf16 v[84:87], v[162:165], v[214:217], v[84:87]
	v_mfma_f32_16x16x32_bf16 v[80:83], v[170:173], v[214:217], v[80:83]
	v_mfma_f32_16x16x32_bf16 v[76:79], v[162:165], v[222:225], v[76:79]
	v_mfma_f32_16x16x32_bf16 v[72:75], v[170:173], v[222:225], v[72:75]
	v_mfma_f32_16x16x32_bf16 v[60:63], v[162:165], v[230:233], v[60:63]
	v_mfma_f32_16x16x32_bf16 v[56:59], v[170:173], v[230:233], v[56:59]
	v_mfma_f32_16x16x32_bf16 v[92:95], v[166:169], v[210:213], v[92:95]
	v_mfma_f32_16x16x32_bf16 v[88:91], v[186:189], v[210:213], v[88:91]
	v_mfma_f32_16x16x32_bf16 v[84:87], v[166:169], v[218:221], v[84:87]
	v_mfma_f32_16x16x32_bf16 v[80:83], v[186:189], v[218:221], v[80:83]
	v_mfma_f32_16x16x32_bf16 v[76:79], v[166:169], v[226:229], v[76:79]
	v_mfma_f32_16x16x32_bf16 v[72:75], v[186:189], v[226:229], v[72:75]
	v_mfma_f32_16x16x32_bf16 v[60:63], v[166:169], v[242:245], v[60:63]
	v_mfma_f32_16x16x32_bf16 v[56:59], v[186:189], v[242:245], v[56:59]
	s_setprio 0
	s_setprio 1
	v_mfma_f32_16x16x32_bf16 v[28:31], v[190:193], v[206:209], v[28:31]
	v_mfma_f32_16x16x32_bf16 v[24:27], v[198:201], v[206:209], v[24:27]
	v_mfma_f32_16x16x32_bf16 v[20:23], v[190:193], v[214:217], v[20:23]
	v_mfma_f32_16x16x32_bf16 v[16:19], v[198:201], v[214:217], v[16:19]
	v_mfma_f32_16x16x32_bf16 v[12:15], v[190:193], v[222:225], v[12:15]
	v_mfma_f32_16x16x32_bf16 v[8:11], v[198:201], v[222:225], v[8:11]
	v_mfma_f32_16x16x32_bf16 v[4:7], v[190:193], v[230:233], v[4:7]
	v_mfma_f32_16x16x32_bf16 v[0:3], v[198:201], v[230:233], v[0:3]
	v_mfma_f32_16x16x32_bf16 v[28:31], v[194:197], v[210:213], v[28:31]
	v_mfma_f32_16x16x32_bf16 v[24:27], v[202:205], v[210:213], v[24:27]
	v_mfma_f32_16x16x32_bf16 v[20:23], v[194:197], v[218:221], v[20:23]
	v_mfma_f32_16x16x32_bf16 v[16:19], v[202:205], v[218:221], v[16:19]
	v_mfma_f32_16x16x32_bf16 v[12:15], v[194:197], v[226:229], v[12:15]
	v_mfma_f32_16x16x32_bf16 v[8:11], v[202:205], v[226:229], v[8:11]
	v_mfma_f32_16x16x32_bf16 v[4:7], v[194:197], v[242:245], v[4:7]
	v_mfma_f32_16x16x32_bf16 v[0:3], v[202:205], v[242:245], v[0:3]
	s_setprio 0
	s_barrier
	s_setprio 2
	s_add_i32 s57, 0, 0x18000
	v_add_u32_e32 v151, s57, v141
	s_add_i32 s58, 0, 0x1c000
	ds_read_b128 v[162:165], v151
	ds_read_b128 v[166:169], v151 offset:1024
	ds_read_b128 v[170:173], v151 offset:2048
	ds_read_b128 v[186:189], v151 offset:3072
	v_add_u32_e32 v151, s58, v141
	ds_read_b128 v[190:193], v151
	ds_read_b128 v[194:197], v151 offset:1024
	ds_read_b128 v[198:201], v151 offset:2048
	ds_read_b128 v[202:205], v151 offset:3072
	s_add_u32 s28, s28, 0x40000
	s_addc_u32 s29, s29, 0
	s_mov_b32 m0, s41
	v_lshl_add_u64 v[182:183], s[28:29], 0, v[134:135]
	ds_read_b128 v[206:209], v150 offset:32768
	ds_read_b128 v[210:213], v150 offset:33792
	ds_read_b128 v[214:217], v150 offset:34816
	ds_read_b128 v[218:221], v150 offset:35840
	ds_read_b128 v[222:225], v150 offset:36864
	ds_read_b128 v[226:229], v150 offset:37888
	ds_read_b128 v[230:233], v150 offset:38912
	ds_read_b128 v[242:245], v150 offset:39936
	global_load_lds_dwordx4 v[182:183], off
	s_mov_b32 m0, s42
	v_lshl_add_u64 v[182:183], s[28:29], 0, v[132:133]
	global_load_lds_dwordx4 v[182:183], off
	s_setprio 0
	s_waitcnt vmcnt(8) lgkmcnt(0)
	s_barrier
	s_setprio 1
	v_mfma_f32_16x16x32_bf16 v[126:129], v[162:165], v[206:209], v[126:129]
	v_mfma_f32_16x16x32_bf16 v[122:125], v[170:173], v[206:209], v[122:125]
	v_mfma_f32_16x16x32_bf16 v[118:121], v[162:165], v[214:217], v[118:121]
	v_mfma_f32_16x16x32_bf16 v[114:117], v[170:173], v[214:217], v[114:117]
	v_mfma_f32_16x16x32_bf16 v[110:113], v[162:165], v[222:225], v[110:113]
	v_mfma_f32_16x16x32_bf16 v[106:109], v[170:173], v[222:225], v[106:109]
	v_mfma_f32_16x16x32_bf16 v[102:105], v[162:165], v[230:233], v[102:105]
	v_mfma_f32_16x16x32_bf16 v[98:101], v[170:173], v[230:233], v[98:101]
	v_mfma_f32_16x16x32_bf16 v[126:129], v[166:169], v[210:213], v[126:129]
	v_mfma_f32_16x16x32_bf16 v[122:125], v[186:189], v[210:213], v[122:125]
	v_mfma_f32_16x16x32_bf16 v[118:121], v[166:169], v[218:221], v[118:121]
	v_mfma_f32_16x16x32_bf16 v[114:117], v[186:189], v[218:221], v[114:117]
	v_mfma_f32_16x16x32_bf16 v[110:113], v[166:169], v[226:229], v[110:113]
	v_mfma_f32_16x16x32_bf16 v[106:109], v[186:189], v[226:229], v[106:109]
	v_mfma_f32_16x16x32_bf16 v[102:105], v[166:169], v[242:245], v[102:105]
	v_mfma_f32_16x16x32_bf16 v[98:101], v[186:189], v[242:245], v[98:101]
	s_setprio 0
	s_setprio 1
	v_mfma_f32_16x16x32_bf16 v[68:71], v[190:193], v[206:209], v[68:71]
	v_mfma_f32_16x16x32_bf16 v[64:67], v[198:201], v[206:209], v[64:67]
	v_mfma_f32_16x16x32_bf16 v[52:55], v[190:193], v[214:217], v[52:55]
	v_mfma_f32_16x16x32_bf16 v[48:51], v[198:201], v[214:217], v[48:51]
	v_mfma_f32_16x16x32_bf16 v[44:47], v[190:193], v[222:225], v[44:47]
	v_mfma_f32_16x16x32_bf16 v[40:43], v[198:201], v[222:225], v[40:43]
	v_mfma_f32_16x16x32_bf16 v[36:39], v[190:193], v[230:233], v[36:39]
	v_mfma_f32_16x16x32_bf16 v[32:35], v[198:201], v[230:233], v[32:35]
	v_mfma_f32_16x16x32_bf16 v[68:71], v[194:197], v[210:213], v[68:71]
	v_mfma_f32_16x16x32_bf16 v[64:67], v[202:205], v[210:213], v[64:67]
	v_mfma_f32_16x16x32_bf16 v[52:55], v[194:197], v[218:221], v[52:55]
	v_mfma_f32_16x16x32_bf16 v[48:51], v[202:205], v[218:221], v[48:51]
	v_mfma_f32_16x16x32_bf16 v[44:47], v[194:197], v[226:229], v[44:47]
	v_mfma_f32_16x16x32_bf16 v[40:43], v[202:205], v[226:229], v[40:43]
	v_mfma_f32_16x16x32_bf16 v[36:39], v[194:197], v[242:245], v[36:39]
	v_mfma_f32_16x16x32_bf16 v[32:35], v[202:205], v[242:245], v[32:35]
	s_setprio 0
	s_barrier
	s_setprio 2
	s_add_i32 s28, s57, s36
	v_lshl_add_u64 v[152:153], v[152:153], 0, s[16:17]
	s_mov_b32 m0, s28
	ds_read_b128 v[206:209], v150 offset:49152
	ds_read_b128 v[210:213], v150 offset:50176
	ds_read_b128 v[214:217], v150 offset:51200
	ds_read_b128 v[218:221], v150 offset:52224
	ds_read_b128 v[222:225], v150 offset:53248
	ds_read_b128 v[226:229], v150 offset:54272
	ds_read_b128 v[230:233], v150 offset:55296
	ds_read_b128 v[242:245], v150 offset:56320
	global_load_lds_dwordx4 v[152:153], off
	s_add_i32 m0, s28, 0x2000
	s_add_u32 s26, s26, 0x40080
	v_lshl_add_u64 v[152:153], v[154:155], 0, s[16:17]
	s_addc_u32 s27, s27, 0
	s_add_i32 s28, s58, s36
	global_load_lds_dwordx4 v[152:153], off
	s_mov_b32 m0, s28
	v_lshl_add_u64 v[152:153], s[26:27], 0, v[96:97]
	global_load_lds_dwordx4 v[152:153], off
	s_add_i32 m0, s28, 0x2000
	v_lshl_add_u64 v[152:153], s[26:27], 0, v[130:131]
	global_load_lds_dwordx4 v[152:153], off
	s_mov_b32 m0, s45
	v_lshl_add_u64 v[152:153], v[156:157], 0, s[16:17]
	global_load_lds_dwordx4 v[152:153], off
	s_mov_b32 m0, s46
	v_lshl_add_u64 v[152:153], v[158:159], 0, s[16:17]
	global_load_lds_dwordx4 v[152:153], off
	s_setprio 0
	s_waitcnt vmcnt(8) lgkmcnt(0)
	s_barrier
	s_setprio 1
	v_mfma_f32_16x16x32_bf16 v[92:95], v[162:165], v[206:209], v[92:95]
	v_mfma_f32_16x16x32_bf16 v[88:91], v[170:173], v[206:209], v[88:91]
	v_mfma_f32_16x16x32_bf16 v[84:87], v[162:165], v[214:217], v[84:87]
	v_mfma_f32_16x16x32_bf16 v[80:83], v[170:173], v[214:217], v[80:83]
	v_mfma_f32_16x16x32_bf16 v[76:79], v[162:165], v[222:225], v[76:79]
	v_mfma_f32_16x16x32_bf16 v[72:75], v[170:173], v[222:225], v[72:75]
	v_mfma_f32_16x16x32_bf16 v[60:63], v[162:165], v[230:233], v[60:63]
	v_mfma_f32_16x16x32_bf16 v[56:59], v[170:173], v[230:233], v[56:59]
	v_mfma_f32_16x16x32_bf16 v[92:95], v[166:169], v[210:213], v[92:95]
	v_mfma_f32_16x16x32_bf16 v[88:91], v[186:189], v[210:213], v[88:91]
	v_mfma_f32_16x16x32_bf16 v[84:87], v[166:169], v[218:221], v[84:87]
	v_mfma_f32_16x16x32_bf16 v[80:83], v[186:189], v[218:221], v[80:83]
	v_mfma_f32_16x16x32_bf16 v[76:79], v[166:169], v[226:229], v[76:79]
	v_mfma_f32_16x16x32_bf16 v[72:75], v[186:189], v[226:229], v[72:75]
	v_mfma_f32_16x16x32_bf16 v[60:63], v[166:169], v[242:245], v[60:63]
	v_mfma_f32_16x16x32_bf16 v[56:59], v[186:189], v[242:245], v[56:59]
	s_setprio 0
	s_setprio 1
	v_mfma_f32_16x16x32_bf16 v[28:31], v[190:193], v[206:209], v[28:31]
	v_mfma_f32_16x16x32_bf16 v[24:27], v[198:201], v[206:209], v[24:27]
	v_mfma_f32_16x16x32_bf16 v[20:23], v[190:193], v[214:217], v[20:23]
	v_mfma_f32_16x16x32_bf16 v[16:19], v[198:201], v[214:217], v[16:19]
	v_mfma_f32_16x16x32_bf16 v[12:15], v[190:193], v[222:225], v[12:15]
	v_mfma_f32_16x16x32_bf16 v[8:11], v[198:201], v[222:225], v[8:11]
	v_mfma_f32_16x16x32_bf16 v[4:7], v[190:193], v[230:233], v[4:7]
	v_mfma_f32_16x16x32_bf16 v[0:3], v[198:201], v[230:233], v[0:3]
	v_mfma_f32_16x16x32_bf16 v[28:31], v[194:197], v[210:213], v[28:31]
	v_mfma_f32_16x16x32_bf16 v[24:27], v[202:205], v[210:213], v[24:27]
	v_mfma_f32_16x16x32_bf16 v[20:23], v[194:197], v[218:221], v[20:23]
	v_mfma_f32_16x16x32_bf16 v[16:19], v[202:205], v[218:221], v[16:19]
	v_mfma_f32_16x16x32_bf16 v[12:15], v[194:197], v[226:229], v[12:15]
	v_mfma_f32_16x16x32_bf16 v[8:11], v[202:205], v[226:229], v[8:11]
	v_mfma_f32_16x16x32_bf16 v[4:7], v[194:197], v[242:245], v[4:7]
	v_mfma_f32_16x16x32_bf16 v[0:3], v[202:205], v[242:245], v[0:3]
	s_setprio 0
	s_barrier
	s_setprio 2
	s_add_i32 s56, s56, 2
	s_add_u32 s14, s14, 0x100
	s_addc_u32 s15, s15, 0
	s_add_u32 s54, s54, 0x100
	s_addc_u32 s55, s55, 0
	s_cmp_gt_u32 s56, 13
	s_cbranch_scc0 .LBB0_393
	s_and_b64 vcc, exec, s[12:13]
	s_cbranch_vccz .LBB0_396
	s_barrier

.LBB0_427:
	s_add_u32 s14, s4, 0xfffc0080
	s_addc_u32 s15, s5, -1
	s_add_i32 s62, 0, 0x10000
	s_cmp_eq_u32 s61, 12
	s_cselect_b32 s37, s29, s15
	s_cselect_b32 s36, s57, s14
	v_add_u32_e32 v154, s62, v169
	s_cselect_b32 s15, s27, s60
	s_cselect_b32 s14, s58, s59
	s_add_i32 s64, 0, 0x14000
	ds_read_b128 v[142:145], v154
	ds_read_b128 v[146:149], v154 offset:1024
	ds_read_b128 v[150:153], v154 offset:2048
	ds_read_b128 v[162:165], v154 offset:3072
	v_add_u32_e32 v154, s64, v169
	ds_read_b128 v[186:189], v154
	ds_read_b128 v[190:193], v154 offset:1024
	ds_read_b128 v[194:197], v154 offset:2048
	ds_read_b128 v[198:201], v154 offset:3072
	v_lshl_add_u64 v[154:155], s[4:5], 0, v[138:139]
	s_add_i32 m0, s43, 0xc000
	ds_read_b128 v[202:205], v173
	ds_read_b128 v[206:209], v173 offset:1024
	ds_read_b128 v[210:213], v173 offset:2048
	ds_read_b128 v[214:217], v173 offset:3072
	ds_read_b128 v[218:221], v173 offset:4096
	ds_read_b128 v[222:225], v173 offset:5120
	ds_read_b128 v[226:229], v173 offset:6144
	ds_read_b128 v[230:233], v173 offset:7168
	global_load_lds_dwordx4 v[154:155], off
	s_add_i32 m0, s43, 0xe000
	v_lshl_add_u64 v[154:155], s[4:5], 0, v[140:141]
	global_load_lds_dwordx4 v[154:155], off
	s_setprio 0
	s_waitcnt vmcnt(8) lgkmcnt(0)
	s_barrier
	s_setprio 1
	v_mfma_f32_16x16x32_bf16 v[126:129], v[142:145], v[202:205], v[126:129]
	v_mfma_f32_16x16x32_bf16 v[122:125], v[150:153], v[202:205], v[122:125]
	v_mfma_f32_16x16x32_bf16 v[110:113], v[142:145], v[210:213], v[110:113]
	v_mfma_f32_16x16x32_bf16 v[106:109], v[150:153], v[210:213], v[106:109]
	v_mfma_f32_16x16x32_bf16 v[92:95], v[142:145], v[218:221], v[92:95]
	v_mfma_f32_16x16x32_bf16 v[88:91], v[150:153], v[218:221], v[88:91]
	v_mfma_f32_16x16x32_bf16 v[76:79], v[142:145], v[226:229], v[76:79]
	v_mfma_f32_16x16x32_bf16 v[72:75], v[150:153], v[226:229], v[72:75]
	v_mfma_f32_16x16x32_bf16 v[126:129], v[146:149], v[206:209], v[126:129]
	v_mfma_f32_16x16x32_bf16 v[122:125], v[162:165], v[206:209], v[122:125]
	v_mfma_f32_16x16x32_bf16 v[110:113], v[146:149], v[214:217], v[110:113]
	v_mfma_f32_16x16x32_bf16 v[106:109], v[162:165], v[214:217], v[106:109]
	v_mfma_f32_16x16x32_bf16 v[92:95], v[146:149], v[222:225], v[92:95]
	v_mfma_f32_16x16x32_bf16 v[88:91], v[162:165], v[222:225], v[88:91]
	v_mfma_f32_16x16x32_bf16 v[76:79], v[146:149], v[230:233], v[76:79]
	v_mfma_f32_16x16x32_bf16 v[72:75], v[162:165], v[230:233], v[72:75]
	s_setprio 0
	s_setprio 1
	v_mfma_f32_16x16x32_bf16 v[118:121], v[186:189], v[202:205], v[118:121]
	v_mfma_f32_16x16x32_bf16 v[114:117], v[194:197], v[202:205], v[114:117]
	v_mfma_f32_16x16x32_bf16 v[102:105], v[186:189], v[210:213], v[102:105]
	v_mfma_f32_16x16x32_bf16 v[98:101], v[194:197], v[210:213], v[98:101]
	v_mfma_f32_16x16x32_bf16 v[84:87], v[186:189], v[218:221], v[84:87]
	v_mfma_f32_16x16x32_bf16 v[80:83], v[194:197], v[218:221], v[80:83]
	v_mfma_f32_16x16x32_bf16 v[68:71], v[186:189], v[226:229], v[68:71]
	v_mfma_f32_16x16x32_bf16 v[64:67], v[194:197], v[226:229], v[64:67]
	v_mfma_f32_16x16x32_bf16 v[118:121], v[190:193], v[206:209], v[118:121]
	v_mfma_f32_16x16x32_bf16 v[114:117], v[198:201], v[206:209], v[114:117]
	v_mfma_f32_16x16x32_bf16 v[102:105], v[190:193], v[214:217], v[102:105]
	v_mfma_f32_16x16x32_bf16 v[98:101], v[198:201], v[214:217], v[98:101]
	v_mfma_f32_16x16x32_bf16 v[84:87], v[190:193], v[222:225], v[84:87]
	v_mfma_f32_16x16x32_bf16 v[80:83], v[198:201], v[222:225], v[80:83]
	v_mfma_f32_16x16x32_bf16 v[68:71], v[190:193], v[230:233], v[68:71]
	v_mfma_f32_16x16x32_bf16 v[64:67], v[198:201], v[230:233], v[64:67]
	s_setprio 0
	s_barrier
	s_setprio 2
	s_add_i32 s62, s62, s42
	v_lshl_add_u64 v[154:155], s[14:15], 0, v[96:97]
	s_mov_b32 m0, s62
	ds_read_b128 v[202:205], v173 offset:16384
	ds_read_b128 v[206:209], v173 offset:17408
	ds_read_b128 v[210:213], v173 offset:18432
	ds_read_b128 v[214:217], v173 offset:19456
	ds_read_b128 v[218:221], v173 offset:20480
	ds_read_b128 v[222:225], v173 offset:21504
	ds_read_b128 v[226:229], v173 offset:22528
	ds_read_b128 v[230:233], v173 offset:23552
	global_load_lds_dwordx4 v[154:155], off
	s_add_i32 m0, s62, 0x2000
	s_add_u32 s62, s14, 0x40000
	v_lshl_add_u64 v[156:157], s[14:15], 0, v[130:131]
	s_addc_u32 s63, s15, 0
	s_add_i32 s64, s64, s42
	global_load_lds_dwordx4 v[156:157], off
	v_lshl_add_u64 v[158:159], s[62:63], 0, v[96:97]
	s_mov_b32 m0, s64
	v_lshl_add_u64 v[166:167], s[36:37], 0, v[132:133]
	global_load_lds_dwordx4 v[158:159], off
	s_add_i32 m0, s64, 0x2000
	v_lshl_add_u64 v[158:159], s[62:63], 0, v[130:131]
	global_load_lds_dwordx4 v[158:159], off
	s_mov_b32 m0, s43
	v_lshl_add_u64 v[158:159], s[36:37], 0, v[134:135]
	global_load_lds_dwordx4 v[158:159], off
	s_mov_b32 m0, s44
	s_nop 0
	global_load_lds_dwordx4 v[166:167], off
	s_setprio 0
	s_waitcnt vmcnt(8) lgkmcnt(0)
	s_barrier
	s_setprio 1
	v_mfma_f32_16x16x32_bf16 v[60:63], v[142:145], v[202:205], v[60:63]
	v_mfma_f32_16x16x32_bf16 v[56:59], v[150:153], v[202:205], v[56:59]
	v_mfma_f32_16x16x32_bf16 v[44:47], v[142:145], v[210:213], v[44:47]
	v_mfma_f32_16x16x32_bf16 v[40:43], v[150:153], v[210:213], v[40:43]
	v_mfma_f32_16x16x32_bf16 v[28:31], v[142:145], v[218:221], v[28:31]
	v_mfma_f32_16x16x32_bf16 v[24:27], v[150:153], v[218:221], v[24:27]
	v_mfma_f32_16x16x32_bf16 v[12:15], v[142:145], v[226:229], v[12:15]
	v_mfma_f32_16x16x32_bf16 v[8:11], v[150:153], v[226:229], v[8:11]
	v_mfma_f32_16x16x32_bf16 v[60:63], v[146:149], v[206:209], v[60:63]
	v_mfma_f32_16x16x32_bf16 v[56:59], v[162:165], v[206:209], v[56:59]
	v_mfma_f32_16x16x32_bf16 v[44:47], v[146:149], v[214:217], v[44:47]
	v_mfma_f32_16x16x32_bf16 v[40:43], v[162:165], v[214:217], v[40:43]
	v_mfma_f32_16x16x32_bf16 v[28:31], v[146:149], v[222:225], v[28:31]
	v_mfma_f32_16x16x32_bf16 v[24:27], v[162:165], v[222:225], v[24:27]
	v_mfma_f32_16x16x32_bf16 v[12:15], v[146:149], v[230:233], v[12:15]
	v_mfma_f32_16x16x32_bf16 v[8:11], v[162:165], v[230:233], v[8:11]
	s_setprio 0
	s_setprio 1
	v_mfma_f32_16x16x32_bf16 v[52:55], v[186:189], v[202:205], v[52:55]
	v_mfma_f32_16x16x32_bf16 v[48:51], v[194:197], v[202:205], v[48:51]
	v_mfma_f32_16x16x32_bf16 v[36:39], v[186:189], v[210:213], v[36:39]
	v_mfma_f32_16x16x32_bf16 v[32:35], v[194:197], v[210:213], v[32:35]
	v_mfma_f32_16x16x32_bf16 v[20:23], v[186:189], v[218:221], v[20:23]
	v_mfma_f32_16x16x32_bf16 v[16:19], v[194:197], v[218:221], v[16:19]
	v_mfma_f32_16x16x32_bf16 v[4:7], v[186:189], v[226:229], v[4:7]
	v_mfma_f32_16x16x32_bf16 v[0:3], v[194:197], v[226:229], v[0:3]
	v_mfma_f32_16x16x32_bf16 v[52:55], v[190:193], v[206:209], v[52:55]
	v_mfma_f32_16x16x32_bf16 v[48:51], v[198:201], v[206:209], v[48:51]
	v_mfma_f32_16x16x32_bf16 v[36:39], v[190:193], v[214:217], v[36:39]
	v_mfma_f32_16x16x32_bf16 v[32:35], v[198:201], v[214:217], v[32:35]
	v_mfma_f32_16x16x32_bf16 v[20:23], v[190:193], v[222:225], v[20:23]
	v_mfma_f32_16x16x32_bf16 v[16:19], v[198:201], v[222:225], v[16:19]
	v_mfma_f32_16x16x32_bf16 v[4:7], v[190:193], v[230:233], v[4:7]
	v_mfma_f32_16x16x32_bf16 v[0:3], v[198:201], v[230:233], v[0:3]
	s_setprio 0
	s_barrier
	s_setprio 2
	s_add_i32 s62, 0, 0x18000
	s_add_i32 s63, 0, 0x1c000
	v_add_u32_e32 v162, s62, v169
	v_add_u32_e32 v182, s63, v169
	ds_read_b128 v[142:145], v162
	ds_read_b128 v[146:149], v162 offset:1024
	ds_read_b128 v[150:153], v162 offset:2048
	ds_read_b128 v[162:165], v162 offset:3072
	ds_read_b128 v[186:189], v182
	ds_read_b128 v[190:193], v182 offset:1024
	ds_read_b128 v[194:197], v182 offset:2048
	ds_read_b128 v[198:201], v182 offset:3072
	s_add_u32 s36, s36, 0x40000
	s_addc_u32 s37, s37, 0
	s_mov_b32 m0, s45
	v_lshl_add_u64 v[182:183], s[36:37], 0, v[134:135]
	ds_read_b128 v[202:205], v173 offset:32768
	ds_read_b128 v[206:209], v173 offset:33792
	ds_read_b128 v[210:213], v173 offset:34816
	ds_read_b128 v[214:217], v173 offset:35840
	ds_read_b128 v[218:221], v173 offset:36864
	ds_read_b128 v[222:225], v173 offset:37888
	ds_read_b128 v[226:229], v173 offset:38912
	ds_read_b128 v[230:233], v173 offset:39936
	global_load_lds_dwordx4 v[182:183], off
	s_mov_b32 m0, s46
	v_lshl_add_u64 v[182:183], s[36:37], 0, v[132:133]
	global_load_lds_dwordx4 v[182:183], off
	s_setprio 0
	s_waitcnt vmcnt(8) lgkmcnt(0)
	s_barrier
	s_setprio 1
	v_mfma_f32_16x16x32_bf16 v[126:129], v[142:145], v[202:205], v[126:129]
	v_mfma_f32_16x16x32_bf16 v[122:125], v[150:153], v[202:205], v[122:125]
	v_mfma_f32_16x16x32_bf16 v[110:113], v[142:145], v[210:213], v[110:113]
	v_mfma_f32_16x16x32_bf16 v[106:109], v[150:153], v[210:213], v[106:109]
	v_mfma_f32_16x16x32_bf16 v[92:95], v[142:145], v[218:221], v[92:95]
	v_mfma_f32_16x16x32_bf16 v[88:91], v[150:153], v[218:221], v[88:91]
	v_mfma_f32_16x16x32_bf16 v[76:79], v[142:145], v[226:229], v[76:79]
	v_mfma_f32_16x16x32_bf16 v[72:75], v[150:153], v[226:229], v[72:75]
	v_mfma_f32_16x16x32_bf16 v[126:129], v[146:149], v[206:209], v[126:129]
	v_mfma_f32_16x16x32_bf16 v[122:125], v[162:165], v[206:209], v[122:125]
	v_mfma_f32_16x16x32_bf16 v[110:113], v[146:149], v[214:217], v[110:113]
	v_mfma_f32_16x16x32_bf16 v[106:109], v[162:165], v[214:217], v[106:109]
	v_mfma_f32_16x16x32_bf16 v[92:95], v[146:149], v[222:225], v[92:95]
	v_mfma_f32_16x16x32_bf16 v[88:91], v[162:165], v[222:225], v[88:91]
	v_mfma_f32_16x16x32_bf16 v[76:79], v[146:149], v[230:233], v[76:79]
	v_mfma_f32_16x16x32_bf16 v[72:75], v[162:165], v[230:233], v[72:75]
	s_setprio 0
	s_setprio 1
	v_mfma_f32_16x16x32_bf16 v[118:121], v[186:189], v[202:205], v[118:121]
	v_mfma_f32_16x16x32_bf16 v[114:117], v[194:197], v[202:205], v[114:117]
	v_mfma_f32_16x16x32_bf16 v[102:105], v[186:189], v[210:213], v[102:105]
	v_mfma_f32_16x16x32_bf16 v[98:101], v[194:197], v[210:213], v[98:101]
	v_mfma_f32_16x16x32_bf16 v[84:87], v[186:189], v[218:221], v[84:87]
	v_mfma_f32_16x16x32_bf16 v[80:83], v[194:197], v[218:221], v[80:83]
	v_mfma_f32_16x16x32_bf16 v[68:71], v[186:189], v[226:229], v[68:71]
	v_mfma_f32_16x16x32_bf16 v[64:67], v[194:197], v[226:229], v[64:67]
	v_mfma_f32_16x16x32_bf16 v[118:121], v[190:193], v[206:209], v[118:121]
	v_mfma_f32_16x16x32_bf16 v[114:117], v[198:201], v[206:209], v[114:117]
	v_mfma_f32_16x16x32_bf16 v[102:105], v[190:193], v[214:217], v[102:105]
	v_mfma_f32_16x16x32_bf16 v[98:101], v[198:201], v[214:217], v[98:101]
	v_mfma_f32_16x16x32_bf16 v[84:87], v[190:193], v[222:225], v[84:87]
	v_mfma_f32_16x16x32_bf16 v[80:83], v[198:201], v[222:225], v[80:83]
	v_mfma_f32_16x16x32_bf16 v[68:71], v[190:193], v[230:233], v[68:71]
	v_mfma_f32_16x16x32_bf16 v[64:67], v[198:201], v[230:233], v[64:67]
	s_setprio 0
	s_barrier
	s_setprio 2
	s_add_i32 s36, s62, s42
	v_lshl_add_u64 v[154:155], v[154:155], 0, s[16:17]
	s_mov_b32 m0, s36
	ds_read_b128 v[202:205], v173 offset:49152
	ds_read_b128 v[206:209], v173 offset:50176
	ds_read_b128 v[210:213], v173 offset:51200
	ds_read_b128 v[214:217], v173 offset:52224
	ds_read_b128 v[218:221], v173 offset:53248
	ds_read_b128 v[222:225], v173 offset:54272
	ds_read_b128 v[226:229], v173 offset:55296
	ds_read_b128 v[230:233], v173 offset:56320
	global_load_lds_dwordx4 v[154:155], off
	s_add_i32 m0, s36, 0x2000
	s_add_u32 s14, s14, 0x40080
	v_lshl_add_u64 v[154:155], v[156:157], 0, s[16:17]
	s_addc_u32 s15, s15, 0
	s_add_i32 s36, s63, s42
	global_load_lds_dwordx4 v[154:155], off
	s_mov_b32 m0, s36
	v_lshl_add_u64 v[154:155], s[14:15], 0, v[96:97]
	global_load_lds_dwordx4 v[154:155], off
	s_add_i32 m0, s36, 0x2000
	v_lshl_add_u64 v[154:155], s[14:15], 0, v[130:131]
	global_load_lds_dwordx4 v[154:155], off
	s_mov_b32 m0, s52
	v_lshl_add_u64 v[154:155], v[158:159], 0, s[16:17]
	global_load_lds_dwordx4 v[154:155], off
	s_mov_b32 m0, s53
	v_lshl_add_u64 v[154:155], v[166:167], 0, s[16:17]
	global_load_lds_dwordx4 v[154:155], off
	s_setprio 0
	s_waitcnt vmcnt(8) lgkmcnt(0)
	s_barrier
	s_setprio 1
	v_mfma_f32_16x16x32_bf16 v[60:63], v[142:145], v[202:205], v[60:63]
	v_mfma_f32_16x16x32_bf16 v[56:59], v[150:153], v[202:205], v[56:59]
	v_mfma_f32_16x16x32_bf16 v[44:47], v[142:145], v[210:213], v[44:47]
	v_mfma_f32_16x16x32_bf16 v[40:43], v[150:153], v[210:213], v[40:43]
	v_mfma_f32_16x16x32_bf16 v[28:31], v[142:145], v[218:221], v[28:31]
	v_mfma_f32_16x16x32_bf16 v[24:27], v[150:153], v[218:221], v[24:27]
	v_mfma_f32_16x16x32_bf16 v[12:15], v[142:145], v[226:229], v[12:15]
	v_mfma_f32_16x16x32_bf16 v[8:11], v[150:153], v[226:229], v[8:11]
	v_mfma_f32_16x16x32_bf16 v[60:63], v[146:149], v[206:209], v[60:63]
	v_mfma_f32_16x16x32_bf16 v[56:59], v[162:165], v[206:209], v[56:59]
	v_mfma_f32_16x16x32_bf16 v[44:47], v[146:149], v[214:217], v[44:47]
	v_mfma_f32_16x16x32_bf16 v[40:43], v[162:165], v[214:217], v[40:43]
	v_mfma_f32_16x16x32_bf16 v[28:31], v[146:149], v[222:225], v[28:31]
	v_mfma_f32_16x16x32_bf16 v[24:27], v[162:165], v[222:225], v[24:27]
	v_mfma_f32_16x16x32_bf16 v[12:15], v[146:149], v[230:233], v[12:15]
	v_mfma_f32_16x16x32_bf16 v[8:11], v[162:165], v[230:233], v[8:11]
	s_setprio 0
	s_setprio 1
	v_mfma_f32_16x16x32_bf16 v[52:55], v[186:189], v[202:205], v[52:55]
	v_mfma_f32_16x16x32_bf16 v[48:51], v[194:197], v[202:205], v[48:51]
	v_mfma_f32_16x16x32_bf16 v[36:39], v[186:189], v[210:213], v[36:39]
	v_mfma_f32_16x16x32_bf16 v[32:35], v[194:197], v[210:213], v[32:35]
	v_mfma_f32_16x16x32_bf16 v[20:23], v[186:189], v[218:221], v[20:23]
	v_mfma_f32_16x16x32_bf16 v[16:19], v[194:197], v[218:221], v[16:19]
	v_mfma_f32_16x16x32_bf16 v[4:7], v[186:189], v[226:229], v[4:7]
	v_mfma_f32_16x16x32_bf16 v[0:3], v[194:197], v[226:229], v[0:3]
	v_mfma_f32_16x16x32_bf16 v[52:55], v[190:193], v[206:209], v[52:55]
	v_mfma_f32_16x16x32_bf16 v[48:51], v[198:201], v[206:209], v[48:51]
	v_mfma_f32_16x16x32_bf16 v[36:39], v[190:193], v[214:217], v[36:39]
	v_mfma_f32_16x16x32_bf16 v[32:35], v[198:201], v[214:217], v[32:35]
	v_mfma_f32_16x16x32_bf16 v[20:23], v[190:193], v[222:225], v[20:23]
	v_mfma_f32_16x16x32_bf16 v[16:19], v[198:201], v[222:225], v[16:19]
	v_mfma_f32_16x16x32_bf16 v[4:7], v[190:193], v[230:233], v[4:7]
	v_mfma_f32_16x16x32_bf16 v[0:3], v[198:201], v[230:233], v[0:3]
	s_setprio 0
	s_barrier
	s_setprio 2
	s_add_i32 s61, s61, 2
	s_add_u32 s4, s4, 0x100
	s_addc_u32 s5, s5, 0
	s_add_u32 s59, s59, 0x100
	s_addc_u32 s60, s60, 0
	s_cmp_gt_u32 s61, 13
	s_cbranch_scc0 .LBB0_427
	s_and_b64 vcc, exec, s[24:25]
	s_cbranch_vccz .LBB0_430
	s_barrier

.LBB0_449:
	s_add_u32 s30, s14, 0xfffc0080
	s_addc_u32 s31, s15, -1
	s_add_i32 s60, 0, 0x10000
	s_cmp_eq_u32 s59, 12
	s_cselect_b32 s35, s25, s31
	s_cselect_b32 s34, s55, s30
	v_add_u32_e32 v96, s60, v151
	s_cselect_b32 s31, s13, s58
	s_cselect_b32 s30, s56, s57
	s_add_i32 s62, 0, 0x14000
	ds_read_b128 v[144:147], v96
	ds_read_b128 v[164:167], v96 offset:1024
	ds_read_b128 v[168:171], v96 offset:2048
	ds_read_b128 v[186:189], v96 offset:3072
	v_add_u32_e32 v96, s62, v151
	ds_read_b128 v[190:193], v96
	ds_read_b128 v[194:197], v96 offset:1024
	ds_read_b128 v[198:201], v96 offset:2048
	ds_read_b128 v[202:205], v96 offset:3072
	v_lshl_add_u64 v[148:149], s[14:15], 0, v[140:141]
	s_add_i32 m0, s41, 0xc000
	ds_read_b128 v[206:209], v163
	ds_read_b128 v[210:213], v163 offset:1024
	ds_read_b128 v[214:217], v163 offset:2048
	ds_read_b128 v[218:221], v163 offset:3072
	ds_read_b128 v[222:225], v163 offset:4096
	ds_read_b128 v[226:229], v163 offset:5120
	ds_read_b128 v[230:233], v163 offset:6144
	ds_read_b128 v[242:245], v163 offset:7168
	global_load_lds_dwordx4 v[148:149], off
	s_add_i32 m0, s41, 0xe000
	v_lshl_add_u64 v[148:149], s[14:15], 0, v[142:143]
	global_load_lds_dwordx4 v[148:149], off
	s_setprio 0
	s_waitcnt vmcnt(8) lgkmcnt(0)
	s_barrier
	s_setprio 1
	v_mfma_f32_16x16x32_bf16 v[126:129], v[144:147], v[206:209], v[126:129]
	v_mfma_f32_16x16x32_bf16 v[122:125], v[168:171], v[206:209], v[122:125]
	v_mfma_f32_16x16x32_bf16 v[110:113], v[144:147], v[214:217], v[110:113]
	v_mfma_f32_16x16x32_bf16 v[106:109], v[168:171], v[214:217], v[106:109]
	v_mfma_f32_16x16x32_bf16 v[92:95], v[144:147], v[222:225], v[92:95]
	v_mfma_f32_16x16x32_bf16 v[88:91], v[168:171], v[222:225], v[88:91]
	v_mfma_f32_16x16x32_bf16 v[76:79], v[144:147], v[230:233], v[76:79]
	v_mfma_f32_16x16x32_bf16 v[72:75], v[168:171], v[230:233], v[72:75]
	v_mfma_f32_16x16x32_bf16 v[126:129], v[164:167], v[210:213], v[126:129]
	v_mfma_f32_16x16x32_bf16 v[122:125], v[186:189], v[210:213], v[122:125]
	v_mfma_f32_16x16x32_bf16 v[110:113], v[164:167], v[218:221], v[110:113]
	v_mfma_f32_16x16x32_bf16 v[106:109], v[186:189], v[218:221], v[106:109]
	v_mfma_f32_16x16x32_bf16 v[92:95], v[164:167], v[226:229], v[92:95]
	v_mfma_f32_16x16x32_bf16 v[88:91], v[186:189], v[226:229], v[88:91]
	v_mfma_f32_16x16x32_bf16 v[76:79], v[164:167], v[242:245], v[76:79]
	v_mfma_f32_16x16x32_bf16 v[72:75], v[186:189], v[242:245], v[72:75]
	s_setprio 0
	s_setprio 1
	v_mfma_f32_16x16x32_bf16 v[118:121], v[190:193], v[206:209], v[118:121]
	v_mfma_f32_16x16x32_bf16 v[114:117], v[198:201], v[206:209], v[114:117]
	v_mfma_f32_16x16x32_bf16 v[102:105], v[190:193], v[214:217], v[102:105]
	v_mfma_f32_16x16x32_bf16 v[98:101], v[198:201], v[214:217], v[98:101]
	v_mfma_f32_16x16x32_bf16 v[84:87], v[190:193], v[222:225], v[84:87]
	v_mfma_f32_16x16x32_bf16 v[80:83], v[198:201], v[222:225], v[80:83]
	v_mfma_f32_16x16x32_bf16 v[68:71], v[190:193], v[230:233], v[68:71]
	v_mfma_f32_16x16x32_bf16 v[64:67], v[198:201], v[230:233], v[64:67]
	v_mfma_f32_16x16x32_bf16 v[118:121], v[194:197], v[210:213], v[118:121]
	v_mfma_f32_16x16x32_bf16 v[114:117], v[202:205], v[210:213], v[114:117]
	v_mfma_f32_16x16x32_bf16 v[102:105], v[194:197], v[218:221], v[102:105]
	v_mfma_f32_16x16x32_bf16 v[98:101], v[202:205], v[218:221], v[98:101]
	v_mfma_f32_16x16x32_bf16 v[84:87], v[194:197], v[226:229], v[84:87]
	v_mfma_f32_16x16x32_bf16 v[80:83], v[202:205], v[226:229], v[80:83]
	v_mfma_f32_16x16x32_bf16 v[68:71], v[194:197], v[242:245], v[68:71]
	v_mfma_f32_16x16x32_bf16 v[64:67], v[202:205], v[242:245], v[64:67]
	s_setprio 0
	s_barrier
	s_setprio 2
	s_add_i32 s60, s60, s40
	v_lshl_add_u64 v[148:149], s[30:31], 0, v[134:135]
	s_mov_b32 m0, s60
	ds_read_b128 v[206:209], v163 offset:16384
	ds_read_b128 v[210:213], v163 offset:17408
	ds_read_b128 v[214:217], v163 offset:18432
	ds_read_b128 v[218:221], v163 offset:19456
	ds_read_b128 v[222:225], v163 offset:20480
	ds_read_b128 v[226:229], v163 offset:21504
	ds_read_b128 v[230:233], v163 offset:22528
	ds_read_b128 v[242:245], v163 offset:23552
	global_load_lds_dwordx4 v[148:149], off
	s_add_i32 m0, s60, 0x2000
	s_add_u32 s60, s30, 0x40000
	v_lshl_add_u64 v[154:155], s[30:31], 0, v[130:131]
	s_addc_u32 s61, s31, 0
	s_add_i32 s62, s62, s40
	global_load_lds_dwordx4 v[154:155], off
	v_lshl_add_u64 v[156:157], s[60:61], 0, v[134:135]
	s_mov_b32 m0, s62
	v_lshl_add_u64 v[158:159], s[34:35], 0, v[132:133]
	global_load_lds_dwordx4 v[156:157], off
	s_add_i32 m0, s62, 0x2000
	v_lshl_add_u64 v[156:157], s[60:61], 0, v[130:131]
	global_load_lds_dwordx4 v[156:157], off
	s_mov_b32 m0, s41
	v_lshl_add_u64 v[156:157], s[34:35], 0, v[136:137]
	global_load_lds_dwordx4 v[156:157], off
	s_mov_b32 m0, s42
	s_nop 0
	global_load_lds_dwordx4 v[158:159], off
	s_setprio 0
	s_waitcnt vmcnt(8) lgkmcnt(0)
	s_barrier
	s_setprio 1
	v_mfma_f32_16x16x32_bf16 v[60:63], v[144:147], v[206:209], v[60:63]
	v_mfma_f32_16x16x32_bf16 v[56:59], v[168:171], v[206:209], v[56:59]
	v_mfma_f32_16x16x32_bf16 v[44:47], v[144:147], v[214:217], v[44:47]
	v_mfma_f32_16x16x32_bf16 v[40:43], v[168:171], v[214:217], v[40:43]
	v_mfma_f32_16x16x32_bf16 v[28:31], v[144:147], v[222:225], v[28:31]
	v_mfma_f32_16x16x32_bf16 v[24:27], v[168:171], v[222:225], v[24:27]
	v_mfma_f32_16x16x32_bf16 v[12:15], v[144:147], v[230:233], v[12:15]
	v_mfma_f32_16x16x32_bf16 v[8:11], v[168:171], v[230:233], v[8:11]
	v_mfma_f32_16x16x32_bf16 v[60:63], v[164:167], v[210:213], v[60:63]
	v_mfma_f32_16x16x32_bf16 v[56:59], v[186:189], v[210:213], v[56:59]
	v_mfma_f32_16x16x32_bf16 v[44:47], v[164:167], v[218:221], v[44:47]
	v_mfma_f32_16x16x32_bf16 v[40:43], v[186:189], v[218:221], v[40:43]
	v_mfma_f32_16x16x32_bf16 v[28:31], v[164:167], v[226:229], v[28:31]
	v_mfma_f32_16x16x32_bf16 v[24:27], v[186:189], v[226:229], v[24:27]
	v_mfma_f32_16x16x32_bf16 v[12:15], v[164:167], v[242:245], v[12:15]
	v_mfma_f32_16x16x32_bf16 v[8:11], v[186:189], v[242:245], v[8:11]
	s_setprio 0
	s_setprio 1
	v_mfma_f32_16x16x32_bf16 v[52:55], v[190:193], v[206:209], v[52:55]
	v_mfma_f32_16x16x32_bf16 v[48:51], v[198:201], v[206:209], v[48:51]
	v_mfma_f32_16x16x32_bf16 v[36:39], v[190:193], v[214:217], v[36:39]
	v_mfma_f32_16x16x32_bf16 v[32:35], v[198:201], v[214:217], v[32:35]
	v_mfma_f32_16x16x32_bf16 v[20:23], v[190:193], v[222:225], v[20:23]
	v_mfma_f32_16x16x32_bf16 v[16:19], v[198:201], v[222:225], v[16:19]
	v_mfma_f32_16x16x32_bf16 v[4:7], v[190:193], v[230:233], v[4:7]
	v_mfma_f32_16x16x32_bf16 v[0:3], v[198:201], v[230:233], v[0:3]
	v_mfma_f32_16x16x32_bf16 v[52:55], v[194:197], v[210:213], v[52:55]
	v_mfma_f32_16x16x32_bf16 v[48:51], v[202:205], v[210:213], v[48:51]
	v_mfma_f32_16x16x32_bf16 v[36:39], v[194:197], v[218:221], v[36:39]
	v_mfma_f32_16x16x32_bf16 v[32:35], v[202:205], v[218:221], v[32:35]
	v_mfma_f32_16x16x32_bf16 v[20:23], v[194:197], v[226:229], v[20:23]
	v_mfma_f32_16x16x32_bf16 v[16:19], v[202:205], v[226:229], v[16:19]
	v_mfma_f32_16x16x32_bf16 v[4:7], v[194:197], v[242:245], v[4:7]
	v_mfma_f32_16x16x32_bf16 v[0:3], v[202:205], v[242:245], v[0:3]
	s_setprio 0
	s_barrier
	s_setprio 2
	s_add_i32 s60, 0, 0x18000
	v_add_u32_e32 v96, s60, v151
	s_add_i32 s61, 0, 0x1c000
	ds_read_b128 v[144:147], v96
	ds_read_b128 v[164:167], v96 offset:1024
	ds_read_b128 v[168:171], v96 offset:2048
	ds_read_b128 v[186:189], v96 offset:3072
	v_add_u32_e32 v96, s61, v151
	ds_read_b128 v[190:193], v96
	ds_read_b128 v[194:197], v96 offset:1024
	ds_read_b128 v[198:201], v96 offset:2048
	ds_read_b128 v[202:205], v96 offset:3072
	s_add_u32 s34, s34, 0x40000
	s_addc_u32 s35, s35, 0
	s_mov_b32 m0, s43
	v_lshl_add_u64 v[172:173], s[34:35], 0, v[136:137]
	ds_read_b128 v[206:209], v163 offset:32768
	ds_read_b128 v[210:213], v163 offset:33792
	ds_read_b128 v[214:217], v163 offset:34816
	ds_read_b128 v[218:221], v163 offset:35840
	ds_read_b128 v[222:225], v163 offset:36864
	ds_read_b128 v[226:229], v163 offset:37888
	ds_read_b128 v[230:233], v163 offset:38912
	ds_read_b128 v[242:245], v163 offset:39936
	global_load_lds_dwordx4 v[172:173], off
	s_mov_b32 m0, s44
	v_lshl_add_u64 v[172:173], s[34:35], 0, v[132:133]
	global_load_lds_dwordx4 v[172:173], off
	s_setprio 0
	s_waitcnt vmcnt(8) lgkmcnt(0)
	s_barrier
	s_setprio 1
	v_mfma_f32_16x16x32_bf16 v[126:129], v[144:147], v[206:209], v[126:129]
	v_mfma_f32_16x16x32_bf16 v[122:125], v[168:171], v[206:209], v[122:125]
	v_mfma_f32_16x16x32_bf16 v[110:113], v[144:147], v[214:217], v[110:113]
	v_mfma_f32_16x16x32_bf16 v[106:109], v[168:171], v[214:217], v[106:109]
	v_mfma_f32_16x16x32_bf16 v[92:95], v[144:147], v[222:225], v[92:95]
	v_mfma_f32_16x16x32_bf16 v[88:91], v[168:171], v[222:225], v[88:91]
	v_mfma_f32_16x16x32_bf16 v[76:79], v[144:147], v[230:233], v[76:79]
	v_mfma_f32_16x16x32_bf16 v[72:75], v[168:171], v[230:233], v[72:75]
	v_mfma_f32_16x16x32_bf16 v[126:129], v[164:167], v[210:213], v[126:129]
	v_mfma_f32_16x16x32_bf16 v[122:125], v[186:189], v[210:213], v[122:125]
	v_mfma_f32_16x16x32_bf16 v[110:113], v[164:167], v[218:221], v[110:113]
	v_mfma_f32_16x16x32_bf16 v[106:109], v[186:189], v[218:221], v[106:109]
	v_mfma_f32_16x16x32_bf16 v[92:95], v[164:167], v[226:229], v[92:95]
	v_mfma_f32_16x16x32_bf16 v[88:91], v[186:189], v[226:229], v[88:91]
	v_mfma_f32_16x16x32_bf16 v[76:79], v[164:167], v[242:245], v[76:79]
	v_mfma_f32_16x16x32_bf16 v[72:75], v[186:189], v[242:245], v[72:75]
	s_setprio 0
	s_setprio 1
	v_mfma_f32_16x16x32_bf16 v[118:121], v[190:193], v[206:209], v[118:121]
	v_mfma_f32_16x16x32_bf16 v[114:117], v[198:201], v[206:209], v[114:117]
	v_mfma_f32_16x16x32_bf16 v[102:105], v[190:193], v[214:217], v[102:105]
	v_mfma_f32_16x16x32_bf16 v[98:101], v[198:201], v[214:217], v[98:101]
	v_mfma_f32_16x16x32_bf16 v[84:87], v[190:193], v[222:225], v[84:87]
	v_mfma_f32_16x16x32_bf16 v[80:83], v[198:201], v[222:225], v[80:83]
	v_mfma_f32_16x16x32_bf16 v[68:71], v[190:193], v[230:233], v[68:71]
	v_mfma_f32_16x16x32_bf16 v[64:67], v[198:201], v[230:233], v[64:67]
	v_mfma_f32_16x16x32_bf16 v[118:121], v[194:197], v[210:213], v[118:121]
	v_mfma_f32_16x16x32_bf16 v[114:117], v[202:205], v[210:213], v[114:117]
	v_mfma_f32_16x16x32_bf16 v[102:105], v[194:197], v[218:221], v[102:105]
	v_mfma_f32_16x16x32_bf16 v[98:101], v[202:205], v[218:221], v[98:101]
	v_mfma_f32_16x16x32_bf16 v[84:87], v[194:197], v[226:229], v[84:87]
	v_mfma_f32_16x16x32_bf16 v[80:83], v[202:205], v[226:229], v[80:83]
	v_mfma_f32_16x16x32_bf16 v[68:71], v[194:197], v[242:245], v[68:71]
	v_mfma_f32_16x16x32_bf16 v[64:67], v[202:205], v[242:245], v[64:67]
	s_setprio 0
	s_barrier
	s_setprio 2
	s_add_i32 s34, s60, s40
	v_lshl_add_u64 v[148:149], v[148:149], 0, s[16:17]
	s_mov_b32 m0, s34
	ds_read_b128 v[206:209], v163 offset:49152
	ds_read_b128 v[210:213], v163 offset:50176
	ds_read_b128 v[214:217], v163 offset:51200
	ds_read_b128 v[218:221], v163 offset:52224
	ds_read_b128 v[222:225], v163 offset:53248
	ds_read_b128 v[226:229], v163 offset:54272
	ds_read_b128 v[230:233], v163 offset:55296
	ds_read_b128 v[242:245], v163 offset:56320
	global_load_lds_dwordx4 v[148:149], off
	s_add_i32 m0, s34, 0x2000
	s_add_u32 s30, s30, 0x40080
	v_lshl_add_u64 v[148:149], v[154:155], 0, s[16:17]
	s_addc_u32 s31, s31, 0
	s_add_i32 s34, s61, s40
	global_load_lds_dwordx4 v[148:149], off
	s_mov_b32 m0, s34
	v_lshl_add_u64 v[148:149], s[30:31], 0, v[134:135]
	global_load_lds_dwordx4 v[148:149], off
	s_add_i32 m0, s34, 0x2000
	v_lshl_add_u64 v[148:149], s[30:31], 0, v[130:131]
	global_load_lds_dwordx4 v[148:149], off
	s_mov_b32 m0, s49
	v_lshl_add_u64 v[148:149], v[156:157], 0, s[16:17]
	global_load_lds_dwordx4 v[148:149], off
	s_mov_b32 m0, s50
	v_lshl_add_u64 v[148:149], v[158:159], 0, s[16:17]
	global_load_lds_dwordx4 v[148:149], off
	s_setprio 0
	s_waitcnt vmcnt(8) lgkmcnt(0)
	s_barrier
	s_setprio 1
	v_mfma_f32_16x16x32_bf16 v[60:63], v[144:147], v[206:209], v[60:63]
	v_mfma_f32_16x16x32_bf16 v[56:59], v[168:171], v[206:209], v[56:59]
	v_mfma_f32_16x16x32_bf16 v[44:47], v[144:147], v[214:217], v[44:47]
	v_mfma_f32_16x16x32_bf16 v[40:43], v[168:171], v[214:217], v[40:43]
	v_mfma_f32_16x16x32_bf16 v[28:31], v[144:147], v[222:225], v[28:31]
	v_mfma_f32_16x16x32_bf16 v[24:27], v[168:171], v[222:225], v[24:27]
	v_mfma_f32_16x16x32_bf16 v[12:15], v[144:147], v[230:233], v[12:15]
	v_mfma_f32_16x16x32_bf16 v[8:11], v[168:171], v[230:233], v[8:11]
	v_mfma_f32_16x16x32_bf16 v[60:63], v[164:167], v[210:213], v[60:63]
	v_mfma_f32_16x16x32_bf16 v[56:59], v[186:189], v[210:213], v[56:59]
	v_mfma_f32_16x16x32_bf16 v[44:47], v[164:167], v[218:221], v[44:47]
	v_mfma_f32_16x16x32_bf16 v[40:43], v[186:189], v[218:221], v[40:43]
	v_mfma_f32_16x16x32_bf16 v[28:31], v[164:167], v[226:229], v[28:31]
	v_mfma_f32_16x16x32_bf16 v[24:27], v[186:189], v[226:229], v[24:27]
	v_mfma_f32_16x16x32_bf16 v[12:15], v[164:167], v[242:245], v[12:15]
	v_mfma_f32_16x16x32_bf16 v[8:11], v[186:189], v[242:245], v[8:11]
	s_setprio 0
	s_setprio 1
	v_mfma_f32_16x16x32_bf16 v[52:55], v[190:193], v[206:209], v[52:55]
	v_mfma_f32_16x16x32_bf16 v[48:51], v[198:201], v[206:209], v[48:51]
	v_mfma_f32_16x16x32_bf16 v[36:39], v[190:193], v[214:217], v[36:39]
	v_mfma_f32_16x16x32_bf16 v[32:35], v[198:201], v[214:217], v[32:35]
	v_mfma_f32_16x16x32_bf16 v[20:23], v[190:193], v[222:225], v[20:23]
	v_mfma_f32_16x16x32_bf16 v[16:19], v[198:201], v[222:225], v[16:19]
	v_mfma_f32_16x16x32_bf16 v[4:7], v[190:193], v[230:233], v[4:7]
	v_mfma_f32_16x16x32_bf16 v[0:3], v[198:201], v[230:233], v[0:3]
	v_mfma_f32_16x16x32_bf16 v[52:55], v[194:197], v[210:213], v[52:55]
	v_mfma_f32_16x16x32_bf16 v[48:51], v[202:205], v[210:213], v[48:51]
	v_mfma_f32_16x16x32_bf16 v[36:39], v[194:197], v[218:221], v[36:39]
	v_mfma_f32_16x16x32_bf16 v[32:35], v[202:205], v[218:221], v[32:35]
	v_mfma_f32_16x16x32_bf16 v[20:23], v[194:197], v[226:229], v[20:23]
	v_mfma_f32_16x16x32_bf16 v[16:19], v[202:205], v[226:229], v[16:19]
	v_mfma_f32_16x16x32_bf16 v[4:7], v[194:197], v[242:245], v[4:7]
	v_mfma_f32_16x16x32_bf16 v[0:3], v[202:205], v[242:245], v[0:3]
	s_setprio 0
	s_barrier
	s_setprio 2
	s_add_i32 s59, s59, 2
	s_add_u32 s14, s14, 0x100
	s_addc_u32 s15, s15, 0
	s_add_u32 s57, s57, 0x100
	s_addc_u32 s58, s58, 0
	s_cmp_gt_u32 s59, 13
	s_cbranch_scc0 .LBB0_449
	s_and_b64 vcc, exec, s[18:19]
	s_cbranch_vccz .LBB0_454
	s_barrier
	v_lshl_add_u32 v146, s54, 8, v150
	s_cmp_gt_i32 s53, 7
	s_mov_b64 s[14:15], -1
	s_cbranch_scc1 .LBB0_455

.LBB0_490:
	s_add_i32 s66, s6, 2
	s_add_u32 s67, s4, 0x80
	s_addc_u32 s7, s5, 0
	s_add_i32 s70, 0, 0x10000
	s_cmp_eq_u32 s60, s6
	s_cselect_b32 s7, s43, s7
	s_cselect_b32 s6, s42, s67
	v_add_u32_e32 v148, s70, v151
	s_cselect_b32 s69, s45, s15
	s_cselect_b32 s68, s44, s14
	s_add_i32 s67, 0, 0x14000
	ds_read_b128 v[140:143], v148
	ds_read_b128 v[144:147], v148 offset:1024
	ds_read_b128 v[162:165], v148 offset:2048
	ds_read_b128 v[166:169], v148 offset:3072
	v_add_u32_e32 v148, s67, v151
	ds_read_b128 v[170:173], v148
	ds_read_b128 v[186:189], v148 offset:1024
	ds_read_b128 v[190:193], v148 offset:2048
	ds_read_b128 v[194:197], v148 offset:3072
	v_lshl_add_u64 v[148:149], s[4:5], 0, v[136:137]
	s_add_i32 m0, s52, 0xc000
	ds_read_b128 v[198:201], v153
	ds_read_b128 v[202:205], v153 offset:1024
	ds_read_b128 v[206:209], v153 offset:2048
	ds_read_b128 v[210:213], v153 offset:3072
	ds_read_b128 v[214:217], v153 offset:4096
	ds_read_b128 v[218:221], v153 offset:5120
	ds_read_b128 v[222:225], v153 offset:6144
	ds_read_b128 v[226:229], v153 offset:7168
	global_load_lds_dwordx4 v[148:149], off
	s_add_i32 m0, s52, 0xe000
	v_lshl_add_u64 v[148:149], s[4:5], 0, v[138:139]
	global_load_lds_dwordx4 v[148:149], off
	s_setprio 0
	s_waitcnt vmcnt(8) lgkmcnt(0)
	s_barrier
	s_setprio 1
	v_mfma_f32_16x16x32_bf16 v[126:129], v[140:143], v[198:201], v[126:129]
	v_mfma_f32_16x16x32_bf16 v[122:125], v[162:165], v[198:201], v[122:125]
	v_mfma_f32_16x16x32_bf16 v[110:113], v[140:143], v[206:209], v[110:113]
	v_mfma_f32_16x16x32_bf16 v[106:109], v[162:165], v[206:209], v[106:109]
	v_mfma_f32_16x16x32_bf16 v[92:95], v[140:143], v[214:217], v[92:95]
	v_mfma_f32_16x16x32_bf16 v[88:91], v[162:165], v[214:217], v[88:91]
	v_mfma_f32_16x16x32_bf16 v[76:79], v[140:143], v[222:225], v[76:79]
	v_mfma_f32_16x16x32_bf16 v[72:75], v[162:165], v[222:225], v[72:75]
	v_mfma_f32_16x16x32_bf16 v[126:129], v[144:147], v[202:205], v[126:129]
	v_mfma_f32_16x16x32_bf16 v[122:125], v[166:169], v[202:205], v[122:125]
	v_mfma_f32_16x16x32_bf16 v[110:113], v[144:147], v[210:213], v[110:113]
	v_mfma_f32_16x16x32_bf16 v[106:109], v[166:169], v[210:213], v[106:109]
	v_mfma_f32_16x16x32_bf16 v[92:95], v[144:147], v[218:221], v[92:95]
	v_mfma_f32_16x16x32_bf16 v[88:91], v[166:169], v[218:221], v[88:91]
	v_mfma_f32_16x16x32_bf16 v[76:79], v[144:147], v[226:229], v[76:79]
	v_mfma_f32_16x16x32_bf16 v[72:75], v[166:169], v[226:229], v[72:75]
	s_setprio 0
	s_setprio 1
	v_mfma_f32_16x16x32_bf16 v[118:121], v[170:173], v[198:201], v[118:121]
	v_mfma_f32_16x16x32_bf16 v[114:117], v[190:193], v[198:201], v[114:117]
	v_mfma_f32_16x16x32_bf16 v[102:105], v[170:173], v[206:209], v[102:105]
	v_mfma_f32_16x16x32_bf16 v[98:101], v[190:193], v[206:209], v[98:101]
	v_mfma_f32_16x16x32_bf16 v[84:87], v[170:173], v[214:217], v[84:87]
	v_mfma_f32_16x16x32_bf16 v[80:83], v[190:193], v[214:217], v[80:83]
	v_mfma_f32_16x16x32_bf16 v[68:71], v[170:173], v[222:225], v[68:71]
	v_mfma_f32_16x16x32_bf16 v[64:67], v[190:193], v[222:225], v[64:67]
	v_mfma_f32_16x16x32_bf16 v[118:121], v[186:189], v[202:205], v[118:121]
	v_mfma_f32_16x16x32_bf16 v[114:117], v[194:197], v[202:205], v[114:117]
	v_mfma_f32_16x16x32_bf16 v[102:105], v[186:189], v[210:213], v[102:105]
	v_mfma_f32_16x16x32_bf16 v[98:101], v[194:197], v[210:213], v[98:101]
	v_mfma_f32_16x16x32_bf16 v[84:87], v[186:189], v[218:221], v[84:87]
	v_mfma_f32_16x16x32_bf16 v[80:83], v[194:197], v[218:221], v[80:83]
	v_mfma_f32_16x16x32_bf16 v[68:71], v[186:189], v[226:229], v[68:71]
	v_mfma_f32_16x16x32_bf16 v[64:67], v[194:197], v[226:229], v[64:67]
	s_setprio 0
	s_barrier
	s_setprio 2
	s_add_i32 s70, s70, s51
	v_lshl_add_u64 v[148:149], s[68:69], 0, v[96:97]
	s_mov_b32 m0, s70
	ds_read_b128 v[198:201], v153 offset:16384
	ds_read_b128 v[202:205], v153 offset:17408
	ds_read_b128 v[206:209], v153 offset:18432
	ds_read_b128 v[210:213], v153 offset:19456
	ds_read_b128 v[214:217], v153 offset:20480
	ds_read_b128 v[218:221], v153 offset:21504
	ds_read_b128 v[222:225], v153 offset:22528
	ds_read_b128 v[226:229], v153 offset:23552
	global_load_lds_dwordx4 v[148:149], off
	s_add_i32 m0, s70, 0x2000
	v_lshl_add_u64 v[154:155], s[68:69], 0, v[130:131]
	s_add_u32 s68, s68, s46
	s_addc_u32 s69, s69, 0
	s_add_i32 s67, s67, s51
	global_load_lds_dwordx4 v[154:155], off
	v_lshl_add_u64 v[156:157], s[68:69], 0, v[96:97]
	s_mov_b32 m0, s67
	v_lshl_add_u64 v[158:159], s[68:69], 0, v[130:131]
	global_load_lds_dwordx4 v[156:157], off
	s_add_i32 m0, s67, 0x2000
	v_lshl_add_u64 v[182:183], s[6:7], 0, v[134:135]
	global_load_lds_dwordx4 v[158:159], off
	s_mov_b32 m0, s52
	v_lshl_add_u64 v[184:185], s[6:7], 0, v[132:133]
	global_load_lds_dwordx4 v[182:183], off
	s_mov_b32 m0, s53
	s_nop 0
	global_load_lds_dwordx4 v[184:185], off
	s_setprio 0
	s_waitcnt vmcnt(8) lgkmcnt(0)
	s_barrier
	s_setprio 1
	v_mfma_f32_16x16x32_bf16 v[60:63], v[140:143], v[198:201], v[60:63]
	v_mfma_f32_16x16x32_bf16 v[56:59], v[162:165], v[198:201], v[56:59]
	v_mfma_f32_16x16x32_bf16 v[44:47], v[140:143], v[206:209], v[44:47]
	v_mfma_f32_16x16x32_bf16 v[40:43], v[162:165], v[206:209], v[40:43]
	v_mfma_f32_16x16x32_bf16 v[28:31], v[140:143], v[214:217], v[28:31]
	v_mfma_f32_16x16x32_bf16 v[24:27], v[162:165], v[214:217], v[24:27]
	v_mfma_f32_16x16x32_bf16 v[12:15], v[140:143], v[222:225], v[12:15]
	v_mfma_f32_16x16x32_bf16 v[8:11], v[162:165], v[222:225], v[8:11]
	v_mfma_f32_16x16x32_bf16 v[60:63], v[144:147], v[202:205], v[60:63]
	v_mfma_f32_16x16x32_bf16 v[56:59], v[166:169], v[202:205], v[56:59]
	v_mfma_f32_16x16x32_bf16 v[44:47], v[144:147], v[210:213], v[44:47]
	v_mfma_f32_16x16x32_bf16 v[40:43], v[166:169], v[210:213], v[40:43]
	v_mfma_f32_16x16x32_bf16 v[28:31], v[144:147], v[218:221], v[28:31]
	v_mfma_f32_16x16x32_bf16 v[24:27], v[166:169], v[218:221], v[24:27]
	v_mfma_f32_16x16x32_bf16 v[12:15], v[144:147], v[226:229], v[12:15]
	v_mfma_f32_16x16x32_bf16 v[8:11], v[166:169], v[226:229], v[8:11]
	s_setprio 0
	s_setprio 1
	v_mfma_f32_16x16x32_bf16 v[52:55], v[170:173], v[198:201], v[52:55]
	v_mfma_f32_16x16x32_bf16 v[48:51], v[190:193], v[198:201], v[48:51]
	v_mfma_f32_16x16x32_bf16 v[36:39], v[170:173], v[206:209], v[36:39]
	v_mfma_f32_16x16x32_bf16 v[32:35], v[190:193], v[206:209], v[32:35]
	v_mfma_f32_16x16x32_bf16 v[20:23], v[170:173], v[214:217], v[20:23]
	v_mfma_f32_16x16x32_bf16 v[16:19], v[190:193], v[214:217], v[16:19]
	v_mfma_f32_16x16x32_bf16 v[4:7], v[170:173], v[222:225], v[4:7]
	v_mfma_f32_16x16x32_bf16 v[0:3], v[190:193], v[222:225], v[0:3]
	v_mfma_f32_16x16x32_bf16 v[52:55], v[186:189], v[202:205], v[52:55]
	v_mfma_f32_16x16x32_bf16 v[48:51], v[194:197], v[202:205], v[48:51]
	v_mfma_f32_16x16x32_bf16 v[36:39], v[186:189], v[210:213], v[36:39]
	v_mfma_f32_16x16x32_bf16 v[32:35], v[194:197], v[210:213], v[32:35]
	v_mfma_f32_16x16x32_bf16 v[20:23], v[186:189], v[218:221], v[20:23]
	v_mfma_f32_16x16x32_bf16 v[16:19], v[194:197], v[218:221], v[16:19]
	v_mfma_f32_16x16x32_bf16 v[4:7], v[186:189], v[226:229], v[4:7]
	v_mfma_f32_16x16x32_bf16 v[0:3], v[194:197], v[226:229], v[0:3]
	s_setprio 0
	s_barrier
	s_setprio 2
	s_add_i32 s67, 0, 0x18000
	s_add_i32 s68, 0, 0x1c000
	v_add_u32_e32 v166, s67, v151
	v_add_u32_e32 v194, s68, v151
	ds_read_b128 v[140:143], v166
	ds_read_b128 v[144:147], v166 offset:1024
	ds_read_b128 v[162:165], v166 offset:2048
	ds_read_b128 v[166:169], v166 offset:3072
	ds_read_b128 v[170:173], v194
	ds_read_b128 v[186:189], v194 offset:1024
	ds_read_b128 v[190:193], v194 offset:2048
	ds_read_b128 v[194:197], v194 offset:3072
	s_add_u32 s6, s6, s46
	s_addc_u32 s7, s7, 0
	s_mov_b32 m0, s54
	v_lshl_add_u64 v[230:231], s[6:7], 0, v[134:135]
	ds_read_b128 v[198:201], v153 offset:32768
	ds_read_b128 v[202:205], v153 offset:33792
	ds_read_b128 v[206:209], v153 offset:34816
	ds_read_b128 v[210:213], v153 offset:35840
	ds_read_b128 v[214:217], v153 offset:36864
	ds_read_b128 v[218:221], v153 offset:37888
	ds_read_b128 v[222:225], v153 offset:38912
	ds_read_b128 v[226:229], v153 offset:39936
	global_load_lds_dwordx4 v[230:231], off
	s_mov_b32 m0, s55
	v_lshl_add_u64 v[230:231], s[6:7], 0, v[132:133]
	global_load_lds_dwordx4 v[230:231], off
	s_setprio 0
	s_waitcnt vmcnt(8) lgkmcnt(0)
	s_barrier
	s_setprio 1
	v_mfma_f32_16x16x32_bf16 v[126:129], v[140:143], v[198:201], v[126:129]
	v_mfma_f32_16x16x32_bf16 v[122:125], v[162:165], v[198:201], v[122:125]
	v_mfma_f32_16x16x32_bf16 v[110:113], v[140:143], v[206:209], v[110:113]
	v_mfma_f32_16x16x32_bf16 v[106:109], v[162:165], v[206:209], v[106:109]
	v_mfma_f32_16x16x32_bf16 v[92:95], v[140:143], v[214:217], v[92:95]
	v_mfma_f32_16x16x32_bf16 v[88:91], v[162:165], v[214:217], v[88:91]
	v_mfma_f32_16x16x32_bf16 v[76:79], v[140:143], v[222:225], v[76:79]
	v_mfma_f32_16x16x32_bf16 v[72:75], v[162:165], v[222:225], v[72:75]
	v_mfma_f32_16x16x32_bf16 v[126:129], v[144:147], v[202:205], v[126:129]
	v_mfma_f32_16x16x32_bf16 v[122:125], v[166:169], v[202:205], v[122:125]
	v_mfma_f32_16x16x32_bf16 v[110:113], v[144:147], v[210:213], v[110:113]
	v_mfma_f32_16x16x32_bf16 v[106:109], v[166:169], v[210:213], v[106:109]
	v_mfma_f32_16x16x32_bf16 v[92:95], v[144:147], v[218:221], v[92:95]
	v_mfma_f32_16x16x32_bf16 v[88:91], v[166:169], v[218:221], v[88:91]
	v_mfma_f32_16x16x32_bf16 v[76:79], v[144:147], v[226:229], v[76:79]
	v_mfma_f32_16x16x32_bf16 v[72:75], v[166:169], v[226:229], v[72:75]
	s_setprio 0
	s_setprio 1
	v_mfma_f32_16x16x32_bf16 v[118:121], v[170:173], v[198:201], v[118:121]
	v_mfma_f32_16x16x32_bf16 v[114:117], v[190:193], v[198:201], v[114:117]
	v_mfma_f32_16x16x32_bf16 v[102:105], v[170:173], v[206:209], v[102:105]
	v_mfma_f32_16x16x32_bf16 v[98:101], v[190:193], v[206:209], v[98:101]
	v_mfma_f32_16x16x32_bf16 v[84:87], v[170:173], v[214:217], v[84:87]
	v_mfma_f32_16x16x32_bf16 v[80:83], v[190:193], v[214:217], v[80:83]
	v_mfma_f32_16x16x32_bf16 v[68:71], v[170:173], v[222:225], v[68:71]
	v_mfma_f32_16x16x32_bf16 v[64:67], v[190:193], v[222:225], v[64:67]
	v_mfma_f32_16x16x32_bf16 v[118:121], v[186:189], v[202:205], v[118:121]
	v_mfma_f32_16x16x32_bf16 v[114:117], v[194:197], v[202:205], v[114:117]
	v_mfma_f32_16x16x32_bf16 v[102:105], v[186:189], v[210:213], v[102:105]
	v_mfma_f32_16x16x32_bf16 v[98:101], v[194:197], v[210:213], v[98:101]
	v_mfma_f32_16x16x32_bf16 v[84:87], v[186:189], v[218:221], v[84:87]
	v_mfma_f32_16x16x32_bf16 v[80:83], v[194:197], v[218:221], v[80:83]
	v_mfma_f32_16x16x32_bf16 v[68:71], v[186:189], v[226:229], v[68:71]
	v_mfma_f32_16x16x32_bf16 v[64:67], v[194:197], v[226:229], v[64:67]
	s_setprio 0
	s_barrier
	s_setprio 2
	s_add_i32 s6, s67, s51
	v_lshl_add_u64 v[148:149], v[148:149], 0, s[16:17]
	s_mov_b32 m0, s6
	ds_read_b128 v[198:201], v153 offset:49152
	ds_read_b128 v[202:205], v153 offset:50176
	ds_read_b128 v[206:209], v153 offset:51200
	ds_read_b128 v[210:213], v153 offset:52224
	ds_read_b128 v[214:217], v153 offset:53248
	ds_read_b128 v[218:221], v153 offset:54272
	ds_read_b128 v[222:225], v153 offset:55296
	ds_read_b128 v[226:229], v153 offset:56320
	global_load_lds_dwordx4 v[148:149], off
	v_lshl_add_u64 v[148:149], v[154:155], 0, s[16:17]
	s_add_i32 m0, s6, 0x2000
	s_add_i32 s6, s68, s51
	global_load_lds_dwordx4 v[148:149], off
	s_mov_b32 m0, s6
	v_lshl_add_u64 v[148:149], v[156:157], 0, s[16:17]
	global_load_lds_dwordx4 v[148:149], off
	s_add_i32 m0, s6, 0x2000
	v_lshl_add_u64 v[148:149], v[158:159], 0, s[16:17]
	global_load_lds_dwordx4 v[148:149], off
	s_mov_b32 m0, s56
	v_lshl_add_u64 v[148:149], v[182:183], 0, s[16:17]
	global_load_lds_dwordx4 v[148:149], off
	s_mov_b32 m0, s57
	v_lshl_add_u64 v[148:149], v[184:185], 0, s[16:17]
	global_load_lds_dwordx4 v[148:149], off
	s_setprio 0
	s_waitcnt vmcnt(8) lgkmcnt(0)
	s_barrier
	s_setprio 1
	v_mfma_f32_16x16x32_bf16 v[60:63], v[140:143], v[198:201], v[60:63]
	v_mfma_f32_16x16x32_bf16 v[56:59], v[162:165], v[198:201], v[56:59]
	v_mfma_f32_16x16x32_bf16 v[44:47], v[140:143], v[206:209], v[44:47]
	v_mfma_f32_16x16x32_bf16 v[40:43], v[162:165], v[206:209], v[40:43]
	v_mfma_f32_16x16x32_bf16 v[28:31], v[140:143], v[214:217], v[28:31]
	v_mfma_f32_16x16x32_bf16 v[24:27], v[162:165], v[214:217], v[24:27]
	v_mfma_f32_16x16x32_bf16 v[12:15], v[140:143], v[222:225], v[12:15]
	v_mfma_f32_16x16x32_bf16 v[8:11], v[162:165], v[222:225], v[8:11]
	v_mfma_f32_16x16x32_bf16 v[60:63], v[144:147], v[202:205], v[60:63]
	v_mfma_f32_16x16x32_bf16 v[56:59], v[166:169], v[202:205], v[56:59]
	v_mfma_f32_16x16x32_bf16 v[44:47], v[144:147], v[210:213], v[44:47]
	v_mfma_f32_16x16x32_bf16 v[40:43], v[166:169], v[210:213], v[40:43]
	v_mfma_f32_16x16x32_bf16 v[28:31], v[144:147], v[218:221], v[28:31]
	v_mfma_f32_16x16x32_bf16 v[24:27], v[166:169], v[218:221], v[24:27]
	v_mfma_f32_16x16x32_bf16 v[12:15], v[144:147], v[226:229], v[12:15]
	v_mfma_f32_16x16x32_bf16 v[8:11], v[166:169], v[226:229], v[8:11]
	s_setprio 0
	s_setprio 1
	v_mfma_f32_16x16x32_bf16 v[52:55], v[170:173], v[198:201], v[52:55]
	v_mfma_f32_16x16x32_bf16 v[48:51], v[190:193], v[198:201], v[48:51]
	v_mfma_f32_16x16x32_bf16 v[36:39], v[170:173], v[206:209], v[36:39]
	v_mfma_f32_16x16x32_bf16 v[32:35], v[190:193], v[206:209], v[32:35]
	v_mfma_f32_16x16x32_bf16 v[20:23], v[170:173], v[214:217], v[20:23]
	v_mfma_f32_16x16x32_bf16 v[16:19], v[190:193], v[214:217], v[16:19]
	v_mfma_f32_16x16x32_bf16 v[4:7], v[170:173], v[222:225], v[4:7]
	v_mfma_f32_16x16x32_bf16 v[0:3], v[190:193], v[222:225], v[0:3]
	v_mfma_f32_16x16x32_bf16 v[52:55], v[186:189], v[202:205], v[52:55]
	v_mfma_f32_16x16x32_bf16 v[48:51], v[194:197], v[202:205], v[48:51]
	v_mfma_f32_16x16x32_bf16 v[36:39], v[186:189], v[210:213], v[36:39]
	v_mfma_f32_16x16x32_bf16 v[32:35], v[194:197], v[210:213], v[32:35]
	v_mfma_f32_16x16x32_bf16 v[20:23], v[186:189], v[218:221], v[20:23]
	v_mfma_f32_16x16x32_bf16 v[16:19], v[194:197], v[218:221], v[16:19]
	v_mfma_f32_16x16x32_bf16 v[4:7], v[186:189], v[226:229], v[4:7]
	v_mfma_f32_16x16x32_bf16 v[0:3], v[194:197], v[226:229], v[0:3]
	s_setprio 0
	s_barrier
	s_setprio 2
	s_add_u32 s4, s4, 0x100
	s_addc_u32 s5, s5, 0
	s_add_u32 s14, s14, 0x100
	s_addc_u32 s15, s15, 0
	s_cmp_ge_u32 s66, s59
	s_mov_b32 s6, s66
	s_cbranch_scc0 .LBB0_490
	s_and_b64 vcc, exec, s[36:37]
	s_cbranch_vccz .LBB0_493
	s_barrier
